# static priority raise: in the two executed prompt-attention loops the per-segment s_setprio flips are replaced by one s_setprio 1 for waves 4-7 before the loop (reset after it)
# speedup vs baseline: 1.0135x; 1.0047x over previous
.LBB0_2449:
	s_setprio 0
	ds_bpermute_b32 v0, v150, v179
	s_add_i32 s90, s90, 1
	s_add_i32 s87, s87, 0x80000
	s_waitcnt lgkmcnt(0)
	v_add_f32_e32 v0, v179, v0
	v_div_scale_f32 v2, s[4:5], v0, v0, 1.0
	v_rcp_f32_e32 v3, v2
	s_lshl_b32 s4, s91, 7
	s_ashr_i32 s5, s4, 31
	s_cmp_lg_u32 s90, s86
	v_fma_f32 v4, -v2, v3, 1.0
	v_fmac_f32_e32 v3, v4, v3
	v_div_scale_f32 v4, vcc, 1.0, v0, 1.0
	v_mul_f32_e32 v5, v4, v3
	v_fma_f32 v6, -v2, v5, v4
	v_fmac_f32_e32 v5, v6, v3
	v_fma_f32 v2, -v2, v5, v4
	v_div_fmas_f32 v2, v2, v3, v5
	v_div_fixup_f32 v8, v2, v0, 1.0
	v_lshlrev_b64 v[2:3], 12, v[146:147]
	v_lshl_add_u64 v[2:3], s[6:7], 0, v[2:3]
	v_lshl_add_u64 v[2:3], s[4:5], 1, v[2:3]
	v_lshlrev_b32_e32 v0, 1, v144
	v_lshl_add_u64 v[6:7], v[2:3], 0, v[0:1]
	v_mul_f32_e32 v0, v64, v8
	v_mul_f32_e32 v2, v65, v8
	v_cvt_pk_bf16_f32 v2, v0, v2
	v_mul_f32_e32 v0, v66, v8
	v_mul_f32_e32 v3, v67, v8
	v_cvt_pk_bf16_f32 v3, v0, v3
	v_mul_f32_e32 v0, v68, v8
	v_mul_f32_e32 v4, v69, v8
	v_mul_f32_e32 v5, v71, v8
	v_cvt_pk_bf16_f32 v4, v0, v4
	v_mul_f32_e32 v0, v70, v8
	v_cvt_pk_bf16_f32 v5, v0, v5
	v_permlane32_swap_b32_e32 v2, v4
	v_permlane32_swap_b32_e32 v3, v5
	global_store_dwordx4 v[6:7], v[2:5], off
	v_mul_f32_e32 v0, v72, v8
	s_nop 0
	v_mul_f32_e32 v2, v73, v8
	v_cvt_pk_bf16_f32 v2, v0, v2
	v_mul_f32_e32 v0, v74, v8
	v_mul_f32_e32 v3, v75, v8
	v_cvt_pk_bf16_f32 v3, v0, v3
	v_mul_f32_e32 v0, v76, v8
	v_mul_f32_e32 v4, v77, v8
	v_mul_f32_e32 v5, v79, v8
	v_cvt_pk_bf16_f32 v4, v0, v4
	v_mul_f32_e32 v0, v78, v8
	v_cvt_pk_bf16_f32 v5, v0, v5
	v_permlane32_swap_b32_e32 v2, v4
	v_permlane32_swap_b32_e32 v3, v5
	global_store_dwordx4 v[6:7], v[2:5], off offset:32
	v_mul_f32_e32 v0, v48, v8
	s_nop 0
	v_mul_f32_e32 v2, v49, v8
	v_cvt_pk_bf16_f32 v2, v0, v2
	v_mul_f32_e32 v0, v50, v8
	v_mul_f32_e32 v3, v51, v8
	v_cvt_pk_bf16_f32 v3, v0, v3
	v_mul_f32_e32 v0, v52, v8
	v_mul_f32_e32 v4, v53, v8
	v_mul_f32_e32 v5, v55, v8
	v_cvt_pk_bf16_f32 v4, v0, v4
	v_mul_f32_e32 v0, v54, v8
	v_cvt_pk_bf16_f32 v5, v0, v5
	v_permlane32_swap_b32_e32 v2, v4
	v_permlane32_swap_b32_e32 v3, v5
	global_store_dwordx4 v[6:7], v[2:5], off offset:64
	v_mul_f32_e32 v0, v56, v8
	s_nop 0
	v_mul_f32_e32 v2, v57, v8
	v_cvt_pk_bf16_f32 v2, v0, v2
	v_mul_f32_e32 v0, v58, v8
	v_mul_f32_e32 v3, v59, v8
	v_cvt_pk_bf16_f32 v3, v0, v3
	v_mul_f32_e32 v0, v60, v8
	v_mul_f32_e32 v4, v61, v8
	v_mul_f32_e32 v5, v63, v8
	v_cvt_pk_bf16_f32 v4, v0, v4
	v_mul_f32_e32 v0, v62, v8
	v_cvt_pk_bf16_f32 v5, v0, v5
	v_permlane32_swap_b32_e32 v2, v4
	v_permlane32_swap_b32_e32 v3, v5
	global_store_dwordx4 v[6:7], v[2:5], off offset:96
	v_mul_f32_e32 v0, v32, v8
	s_nop 0
	v_mul_f32_e32 v2, v33, v8
	v_cvt_pk_bf16_f32 v2, v0, v2
	v_mul_f32_e32 v0, v34, v8
	v_mul_f32_e32 v3, v35, v8
	v_cvt_pk_bf16_f32 v3, v0, v3
	v_mul_f32_e32 v0, v36, v8
	v_mul_f32_e32 v4, v37, v8
	v_mul_f32_e32 v5, v39, v8
	v_cvt_pk_bf16_f32 v4, v0, v4
	v_mul_f32_e32 v0, v38, v8
	v_cvt_pk_bf16_f32 v5, v0, v5
	v_permlane32_swap_b32_e32 v2, v4
	v_permlane32_swap_b32_e32 v3, v5
	global_store_dwordx4 v[6:7], v[2:5], off offset:128
	v_mul_f32_e32 v0, v40, v8
	s_nop 0
	v_mul_f32_e32 v2, v41, v8
	v_cvt_pk_bf16_f32 v2, v0, v2
	v_mul_f32_e32 v0, v42, v8
	v_mul_f32_e32 v3, v43, v8
	v_cvt_pk_bf16_f32 v3, v0, v3
	v_mul_f32_e32 v0, v44, v8
	v_mul_f32_e32 v4, v45, v8
	v_mul_f32_e32 v5, v47, v8
	v_cvt_pk_bf16_f32 v4, v0, v4
	v_mul_f32_e32 v0, v46, v8
	v_cvt_pk_bf16_f32 v5, v0, v5
	v_permlane32_swap_b32_e32 v2, v4
	v_permlane32_swap_b32_e32 v3, v5
	global_store_dwordx4 v[6:7], v[2:5], off offset:160
	v_mul_f32_e32 v0, v16, v8
	s_nop 0
	v_mul_f32_e32 v2, v17, v8
	v_cvt_pk_bf16_f32 v2, v0, v2
	v_mul_f32_e32 v0, v18, v8
	v_mul_f32_e32 v3, v19, v8
	v_cvt_pk_bf16_f32 v3, v0, v3
	v_mul_f32_e32 v0, v20, v8
	v_mul_f32_e32 v4, v21, v8
	v_mul_f32_e32 v5, v23, v8
	v_cvt_pk_bf16_f32 v4, v0, v4
	v_mul_f32_e32 v0, v22, v8
	v_cvt_pk_bf16_f32 v5, v0, v5
	v_permlane32_swap_b32_e32 v2, v4
	v_permlane32_swap_b32_e32 v3, v5
	global_store_dwordx4 v[6:7], v[2:5], off offset:192
	v_mul_f32_e32 v0, v24, v8
	s_nop 0
	v_mul_f32_e32 v2, v25, v8
	v_cvt_pk_bf16_f32 v2, v0, v2
	v_mul_f32_e32 v0, v26, v8
	v_mul_f32_e32 v3, v27, v8
	v_cvt_pk_bf16_f32 v3, v0, v3
	v_mul_f32_e32 v0, v28, v8
	v_mul_f32_e32 v4, v29, v8
	v_mul_f32_e32 v5, v31, v8
	v_cvt_pk_bf16_f32 v4, v0, v4
	v_mul_f32_e32 v0, v30, v8
	v_cvt_pk_bf16_f32 v5, v0, v5
	v_permlane32_swap_b32_e32 v2, v4
	v_permlane32_swap_b32_e32 v3, v5
	global_store_dwordx4 v[6:7], v[2:5], off offset:224
	s_cbranch_scc0 .LBB0_2491
.LBB0_2450:
	v_mov_b32_e32 v0, v1
	s_movk_i32 s2, 0xffc0
	v_mbcnt_lo_u32_b32 v0, -1, v0
	v_mbcnt_hi_u32_b32 v0, -1, v0
	v_add_u32_e32 v4, s33, v0
	s_nop 0
	v_readfirstlane_b32 s1, v4
	s_nop 1
	v_mov_b32_e32 v0, s1
	v_bfi_b32 v0, s2, v0, v4
	v_mul_hi_i32 v2, v0, s70
	v_lshrrev_b32_e32 v3, 31, v2
	v_ashrrev_i32_e32 v2, 2, v2
	v_add_u32_e32 v2, v2, v3
	v_lshlrev_b32_e32 v3, 1, v2
	v_mad_u64_u32 v[6:7], s[4:5], v2, s71, v[0:1]
	v_and_b32_e32 v3, 4, v3
	v_bfe_u32 v5, v2, 2, 2
	v_bitop3_b32 v5, v3, v6, v5 bitop3:0x36
	v_cmp_lt_i32_e32 vcc, 15, v5
	s_and_saveexec_b64 s[4:5], vcc
	s_xor_b64 s[4:5], exec, s[4:5]
	v_mul_lo_u32 v2, v2, s72
	v_add_u32_e32 v6, s97, v2
	s_or_saveexec_b64 s[4:5], s[4:5]
	s_add_i32 s91, s90, s95
	s_lshl_b32 s2, s91, 19
	s_add_i32 s2, s2, s11
	s_add_i32 s8, s2, 0x639ff300
	v_mov_b32_e32 v3, 1
	s_xor_b64 exec, exec, s[4:5]
	v_lshl_add_u32 v6, v2, 8, s8
	v_mov_b32_e32 v3, 0
	s_or_b64 exec, exec, s[4:5]
	v_add_u32_e32 v2, 0x200, v0
	v_mul_hi_i32 v7, v2, s70
	v_lshrrev_b32_e32 v8, 31, v7
	v_ashrrev_i32_e32 v7, 2, v7
	v_add_u32_e32 v9, v7, v8
	v_lshlrev_b32_e32 v7, 1, v9
	v_mad_u64_u32 v[10:11], s[4:5], v9, s71, v[2:3]
	v_and_b32_e32 v7, 4, v7
	v_bfe_u32 v8, v9, 2, 2
	v_bitop3_b32 v7, v7, v10, v8 bitop3:0x36
	v_cmp_lt_i32_e32 vcc, 15, v7
	s_and_saveexec_b64 s[4:5], vcc
	s_xor_b64 s[4:5], exec, s[4:5]
	v_mul_lo_u32 v8, v9, s72
	v_add_u32_e32 v8, s97, v8
	v_or_b32_e32 v3, 2, v3
	s_andn2_saveexec_b64 s[4:5], s[4:5]
	v_lshl_add_u32 v8, v9, 8, s8
	s_or_b64 exec, exec, s[4:5]
	v_add_u32_e32 v10, 0x400, v0
	v_mul_hi_i32 v9, v10, s70
	v_lshrrev_b32_e32 v11, 31, v9
	v_ashrrev_i32_e32 v9, 2, v9
	v_add_u32_e32 v11, v9, v11
	v_lshlrev_b32_e32 v9, 1, v11
	v_mad_u64_u32 v[12:13], s[4:5], v11, s71, v[10:11]
	v_and_b32_e32 v9, 4, v9
	v_bfe_u32 v10, v11, 2, 2
	v_bitop3_b32 v9, v9, v12, v10 bitop3:0x36
	v_cmp_lt_i32_e32 vcc, 15, v9
	s_and_saveexec_b64 s[4:5], vcc
	s_xor_b64 s[4:5], exec, s[4:5]
	v_mul_lo_u32 v10, v11, s72
	v_add_u32_e32 v10, s97, v10
	v_or_b32_e32 v3, 4, v3
	s_andn2_saveexec_b64 s[4:5], s[4:5]
	v_lshl_add_u32 v10, v11, 8, s8
	s_or_b64 exec, exec, s[4:5]
	v_ashrrev_i32_e32 v0, 4, v0
	v_lshl_add_u32 v145, v7, 4, v8
	v_lshlrev_b32_e32 v7, 2, v0
	v_lshl_add_u32 v148, v5, 4, v6
	v_and_b32_e32 v6, 15, v4
	v_and_b32_e32 v7, 12, v7
	v_bfe_u32 v8, v0, 2, 2
	v_bitop3_b32 v7, v7, v6, v8 bitop3:0x36
	v_ashrrev_i32_e32 v2, 4, v2
	v_lshl_add_u32 v149, v9, 4, v10
	v_lshlrev_b32_e32 v9, 4, v7
	v_lshlrev_b32_e32 v7, 2, v2
	s_bitcmp0_b32 s90, 0
	v_and_b32_e32 v7, 12, v7
	v_bfe_u32 v10, v2, 2, 2
	s_cselect_b32 s4, s85, s10
	s_ashr_i32 s5, s1, 6
	s_add_i32 s2, s2, 0x679ff300
	v_lshlrev_b32_e32 v8, 8, v0
	v_bitop3_b32 v6, v7, v6, v10 bitop3:0x36
	v_lshlrev_b32_e32 v2, 8, v2
	v_add_u32_e32 v0, s2, v8
	v_lshlrev_b32_e32 v10, 4, v6
	v_add_u32_e32 v6, s2, v2
	s_lshl_b32 s2, s5, 10
	s_add_i32 s49, s2, 0
	s_waitcnt lgkmcnt(0)
	s_barrier
	s_mov_b32 m0, s49
	s_add_i32 s93, s49, 0x2000
	s_lshl_b32 s1, s5, 5
	s_lshl_b32 s48, s4, 2
	s_lshl_b32 s4, s4, 8
	global_load_lds_dwordx4 v148, s[82:83]
	s_mov_b32 m0, s93
	s_add_i32 s74, s49, 0x4000
	s_add_i32 s1, s1, s4
	global_load_lds_dwordx4 v145, s[82:83]
	s_mov_b32 m0, s74
	s_add_i32 s75, s49, 0xc000
	s_add_i32 s48, s48, 4
	v_or_b32_e32 v0, v9, v0
	global_load_lds_dwordx4 v149, s[82:83]
	s_mov_b32 m0, s75
	s_add_i32 s76, s49, 0xe000
	s_ashr_i32 s2, s1, 31
	v_and_b32_e32 v5, 31, v4
	v_or_b32_e32 v6, v10, v6
	global_load_lds_dwordx4 v0, s[82:83]
	s_mov_b32 m0, s76
	s_add_u32 s4, s1, s96
	global_load_lds_dwordx4 v6, s[82:83]
	v_or_b32_e32 v146, s4, v5
	v_mov_b64_e32 v[6:7], s[44:45]
	s_movk_i32 s4, 0x1800
	v_mad_u64_u32 v[6:7], s[4:5], v146, s4, v[6:7]
	s_addc_u32 s2, s2, 0
	v_lshrrev_b32_e32 v0, 2, v4
	s_mul_i32 s4, s91, 0xc0
	v_and_b32_e32 v144, 8, v0
	v_mad_i32_i24 v7, s2, v158, v7
	s_ashr_i32 s5, s4, 31
	v_lshl_add_u64 v[6:7], s[4:5], 1, v[6:7]
	v_lshlrev_b32_e32 v0, 1, v144
	v_lshl_add_u64 v[6:7], v[6:7], 0, v[0:1]
	global_load_dwordx4 v[96:99], v[6:7], off offset:352
	global_load_dwordx4 v[100:103], v[6:7], off offset:320
	global_load_dwordx4 v[104:107], v[6:7], off offset:288
	global_load_dwordx4 v[108:111], v[6:7], off offset:256
	global_load_dwordx4 v[112:115], v[6:7], off offset:224
	global_load_dwordx4 v[116:119], v[6:7], off offset:192
	global_load_dwordx4 v[120:123], v[6:7], off offset:160
	global_load_dwordx4 v[124:127], v[6:7], off offset:128
	global_load_dwordx4 v[128:131], v[6:7], off offset:96
	global_load_dwordx4 v[132:135], v[6:7], off offset:64
	global_load_dwordx4 v[136:139], v[6:7], off offset:32
	global_load_dwordx4 v[140:143], v[6:7], off
	v_and_b32_e32 v11, 63, v4
	v_lshlrev_b32_e32 v7, 1, v11
	v_lshrrev_b32_e32 v0, 5, v11
	v_bfe_u32 v6, v4, 2, 2
	v_and_b32_e32 v7, 4, v7
	v_or_b32_e32 v17, 2, v0
	v_bitop3_b32 v20, v7, v0, v6 bitop3:0x36
	v_lshlrev_b32_e32 v152, 4, v20
	v_bitop3_b32 v20, v7, v17, v6 bitop3:0x36
	v_lshlrev_b32_e32 v153, 4, v20
	v_or_b32_e32 v20, 4, v0
	v_bitop3_b32 v20, v7, v20, v6 bitop3:0x36
	v_lshlrev_b32_e32 v154, 4, v20
	v_or_b32_e32 v20, 6, v0
	v_bitop3_b32 v20, v7, v20, v6 bitop3:0x36
	v_lshlrev_b32_e32 v155, 4, v20
	v_or_b32_e32 v20, 8, v0
	v_bitop3_b32 v20, v7, v20, v6 bitop3:0x36
	v_lshlrev_b32_e32 v156, 4, v20
	v_or_b32_e32 v20, 10, v0
	v_bitop3_b32 v20, v7, v20, v6 bitop3:0x36
	v_lshlrev_b32_e32 v157, 4, v20
	v_or_b32_e32 v20, 12, v0
	v_bitop3_b32 v20, v7, v20, v6 bitop3:0x36
	v_lshlrev_b32_e32 v164, 4, v20
	v_or_b32_e32 v20, 14, v0
	v_bitop3_b32 v20, v7, v20, v6 bitop3:0x36
	v_lshlrev_b32_e32 v165, 4, v20
	v_or_b32_e32 v20, 16, v0
	v_bitop3_b32 v20, v7, v20, v6 bitop3:0x36
	v_lshlrev_b32_e32 v166, 4, v20
	v_or_b32_e32 v20, 18, v0
	v_bitop3_b32 v20, v7, v20, v6 bitop3:0x36
	v_lshlrev_b32_e32 v167, 4, v20
	v_or_b32_e32 v20, 20, v0
	v_bitop3_b32 v20, v7, v20, v6 bitop3:0x36
	v_lshlrev_b32_e32 v168, 4, v20
	v_or_b32_e32 v20, 22, v0
	v_lshlrev_b32_e32 v12, 2, v0
	v_bitop3_b32 v7, v7, v20, v6 bitop3:0x36
	v_lshlrev_b32_e32 v169, 4, v7
	v_or_b32_e32 v7, 2, v12
	v_cmp_gt_u32_e64 s[14:15], v7, v5
	v_or_b32_e32 v7, 3, v12
	v_cmp_gt_u32_e64 s[16:17], v7, v5
	v_or_b32_e32 v7, 9, v12
	v_cmp_gt_u32_e64 s[20:21], v7, v5
	v_or_b32_e32 v7, 10, v12
	v_cmp_gt_u32_e64 s[22:23], v7, v5
	v_or_b32_e32 v7, 11, v12
	v_cmp_gt_u32_e64 s[24:25], v7, v5
	v_or_b32_e32 v7, 17, v12
	v_cmp_gt_u32_e64 s[28:29], v7, v5
	v_or_b32_e32 v7, 18, v12
	v_cmp_gt_u32_e64 s[30:31], v7, v5
	v_or_b32_e32 v7, 19, v12
	v_cmp_gt_u32_e64 s[34:35], v7, v5
	v_or_b32_e32 v7, 24, v12
	v_cmp_gt_u32_e64 s[36:37], v7, v5
	v_or_b32_e32 v7, 25, v12
	v_lshlrev_b32_e32 v13, 2, v11
	v_cmp_gt_u32_e64 s[38:39], v7, v5
	v_or_b32_e32 v7, 26, v12
	v_xor_b32_e32 v150, 0x80, v13
	v_lshrrev_b32_e32 v13, 3, v4
	v_bfe_u32 v14, v4, 1, 1
	v_or_b32_e32 v15, 16, v12
	v_or_b32_e32 v18, 8, v12
	v_cmp_gt_u32_e64 s[40:41], v7, v5
	v_or_b32_e32 v7, 27, v12
	v_and_b32_e32 v4, 12, v4
	v_and_or_b32 v13, v13, 2, v14
	v_lshlrev_b32_e32 v14, 3, v11
	v_mad_u32_u24 v151, v5, s73, 0
	v_cmp_gt_u32_e64 s[8:9], v12, v5
	v_cmp_lt_u32_e64 s[12:13], v12, v5
	v_cmp_gt_u32_e64 s[18:19], v18, v5
	v_cmp_gt_u32_e64 s[26:27], v15, v5
	v_cmp_gt_u32_e64 s[42:43], v7, v5
	v_or_b32_e32 v5, v12, v6
	v_or_b32_e32 v7, v0, v4
	v_and_b32_e32 v16, 8, v14
	v_lshlrev_b32_e32 v14, 2, v6
	v_lshrrev_b32_e32 v19, 2, v18
	v_lshlrev_b32_e32 v5, 8, v5
	v_or_b32_e32 v26, 4, v13
	v_bitop3_b32 v27, v13, v7, 4 bitop3:0x36
	v_or_b32_e32 v31, 8, v13
	v_bitop3_b32 v32, v13, v7, 8 bitop3:0x36
	v_or_b32_e32 v36, 12, v13
	v_bitop3_b32 v7, v13, v7, 12 bitop3:0x36
	v_or_b32_e32 v15, v15, v6
	v_bitop3_b32 v4, v0, v13, v4 bitop3:0x36
	v_add_u32_e32 v20, 0, v5
	v_or_b32_e32 v22, v18, v6
	v_bitop3_b32 v23, v19, v13, v14 bitop3:0x36
	v_bitop3_b32 v29, v19, v26, v14 bitop3:0x36
	v_bitop3_b32 v34, v19, v31, v14 bitop3:0x36
	v_lshlrev_b32_e32 v7, 4, v7
	v_bitop3_b32 v19, v19, v36, v14 bitop3:0x36
	v_bitop3_b32 v38, v14, v13, v0 bitop3:0x36
	v_lshlrev_b32_e32 v15, 8, v15
	v_bitop3_b32 v13, v14, v13, v17 bitop3:0x36
	v_bitop3_b32 v42, v14, v26, v0 bitop3:0x36
	v_bitop3_b32 v26, v14, v26, v17 bitop3:0x36
	v_bitop3_b32 v45, v14, v31, v0 bitop3:0x36
	v_bitop3_b32 v31, v14, v31, v17 bitop3:0x36
	v_bitop3_b32 v0, v14, v36, v0 bitop3:0x36
	v_bitop3_b32 v14, v14, v36, v17 bitop3:0x36
	v_or_b32_e32 v11, 32, v11
	v_or_b32_e32 v6, 32, v6
	v_add_u32_e32 v5, s62, v5
	v_lshlrev_b32_e32 v4, 4, v4
	v_lshlrev_b32_e32 v27, 4, v27
	v_lshlrev_b32_e32 v32, 4, v32
	v_add_u32_e32 v37, v20, v7
	v_lshlrev_b32_e32 v19, 4, v19
	v_add_u32_e32 v39, 0, v15
	v_lshlrev_b32_e32 v38, 4, v38
	v_lshlrev_b32_e32 v13, 4, v13
	v_lshlrev_b32_e32 v42, 4, v42
	v_lshlrev_b32_e32 v26, 4, v26
	v_lshlrev_b32_e32 v45, 4, v45
	v_lshlrev_b32_e32 v31, 4, v31
	v_lshlrev_b32_e32 v0, 4, v0
	v_lshlrev_b32_e32 v14, 4, v14
	v_mad_u32_u24 v170, v11, s73, 0
	v_or_b32_e32 v11, v6, v12
	v_add_u32_e32 v61, v5, v7
	v_add_u32_e32 v7, s62, v15
	v_add_u32_e32 v21, v20, v4
	v_add_u32_e32 v28, v20, v27
	v_add_u32_e32 v33, v20, v32
	v_add_u32_e32 v40, v39, v38
	v_add_u32_e32 v41, v20, v13
	v_add_u32_e32 v43, v39, v42
	v_add_u32_e32 v44, v20, v26
	v_add_u32_e32 v46, v39, v45
	v_add_u32_e32 v47, v20, v31
	v_add_u32_e32 v39, v39, v0
	v_add_u32_e32 v17, v20, v14
	v_lshlrev_b32_e32 v11, 8, v11
	v_or_b32_e32 v6, v18, v6
	v_add_u32_e32 v52, v20, v19
	v_add_u32_e32 v53, v20, v38
	v_add_u32_e32 v54, v20, v42
	v_add_u32_e32 v55, v20, v45
	v_add_u32_e32 v20, v20, v0
	v_add_u32_e32 v67, v7, v0
	v_add_u32_e32 v70, v5, v0
	v_and_b32_e32 v0, 1, v3
	v_lshlrev_b32_e32 v22, 8, v22
	v_add_u32_e32 v12, 0, v11
	v_lshlrev_b32_e32 v6, 8, v6
	v_add_u32_e32 v63, v7, v38
	v_add_u32_e32 v65, v7, v42
	v_add_u32_e32 v66, v7, v45
	v_add_u32_e32 v7, s62, v11
	v_cmp_eq_u32_e32 vcc, 0, v0
	v_and_b32_e32 v0, 2, v3
	v_add_u32_e32 v24, 0, v22
	v_lshlrev_b32_e32 v23, 4, v23
	v_lshlrev_b32_e32 v29, 4, v29
	v_lshlrev_b32_e32 v34, 4, v34
	v_add_u32_e32 v36, v12, v4
	v_add_u32_e32 v18, 0, v6
	v_add_u32_e32 v49, v12, v27
	v_add_u32_e32 v51, v12, v32
	v_add_u32_e32 v56, v5, v4
	v_add_u32_e32 v12, s62, v22
	v_add_u32_e32 v69, v7, v4
	v_add_u32_e32 v4, s62, v6
	v_cndmask_b32_e32 v171, v159, v160, vcc
	v_cmp_eq_u32_e32 vcc, 0, v0
	v_and_b32_e32 v0, 4, v3
	v_add_u32_e32 v25, v24, v23
	v_add_u32_e32 v30, v24, v29
	v_add_u32_e32 v35, v24, v34
	v_add_u32_e32 v24, v24, v19
	v_add_u32_e32 v48, v18, v23
	v_add_u32_e32 v50, v18, v29
	v_add_u32_e32 v18, v18, v34
	v_add_u32_e32 v22, v12, v23
	v_add_u32_e32 v57, v5, v27
	v_add_u32_e32 v58, v12, v29
	v_add_u32_e32 v59, v5, v32
	v_add_u32_e32 v60, v12, v34
	v_add_u32_e32 v62, v12, v19
	v_add_u32_e32 v64, v5, v13
	v_add_u32_e32 v26, v5, v26
	v_add_u32_e32 v31, v5, v31
	v_add_u32_e32 v68, v5, v14
	v_add_u32_e32 v23, v4, v23
	v_add_u32_e32 v27, v7, v27
	v_add_u32_e32 v29, v4, v29
	v_add_u32_e32 v32, v7, v32
	v_add_u32_e32 v34, v4, v34
	v_add_u32_e32 v19, v5, v19
	v_add_u32_e32 v38, v5, v38
	v_add_u32_e32 v42, v5, v42
	v_add_u32_e32 v45, v5, v45
	v_cndmask_b32_e32 v172, v159, v160, vcc
	v_cmp_eq_u32_e32 vcc, 0, v0
	v_mov_b32_e32 v14, v1
	v_mov_b32_e32 v15, v1
	v_cndmask_b32_e32 v173, v159, v160, vcc
	v_or_b32_e32 v177, v2, v10
	v_or_b32_e32 v178, v8, v9
	v_mov_b32_e32 v0, v1
	v_mov_b32_e32 v2, v1
	v_mov_b32_e32 v3, v1
	v_mov_b32_e32 v4, v1
	v_mov_b32_e32 v5, v1
	v_mov_b32_e32 v6, v1
	v_mov_b32_e32 v7, v1
	v_mov_b32_e32 v8, v1
	v_mov_b32_e32 v9, v1
	v_mov_b32_e32 v10, v1
	v_mov_b32_e32 v11, v1
	v_mov_b32_e32 v12, v1
	v_mov_b32_e32 v13, v1
	v_add_u32_e32 v180, v21, v16
	v_add_u32_e32 v181, v25, v16
	v_add_u32_e32 v182, v28, v16
	v_add_u32_e32 v183, v30, v16
	v_add_u32_e32 v184, v33, v16
	v_add_u32_e32 v185, v35, v16
	v_add_u32_e32 v186, v24, v16
	v_add_u32_e32 v187, v40, v16
	v_add_u32_e32 v188, v43, v16
	v_add_u32_e32 v189, v46, v16
	v_add_u32_e32 v190, v39, v16
	v_add_u32_e32 v191, v36, v16
	v_add_u32_e32 v235, v48, v16
	v_add_u32_e32 v252, v49, v16
	v_add_u32_e32 v253, v50, v16
	v_add_u32_e32 v254, v51, v16
	v_add_u32_e32 v196, v18, v16
	v_add_u32_e32 v197, v52, v16
	v_add_u32_e32 v198, v53, v16
	v_add_u32_e32 v199, v54, v16
	v_add_u32_e32 v200, v55, v16
	v_add_u32_e32 v201, v20, v16
	v_add_u32_e32 v202, v56, v16
	v_add_u32_e32 v203, v22, v16
	v_add_u32_e32 v204, v57, v16
	v_add_u32_e32 v205, v58, v16
	v_add_u32_e32 v206, v59, v16
	v_add_u32_e32 v207, v60, v16
	v_add_u32_e32 v208, v62, v16
	v_add_u32_e32 v209, v63, v16
	v_add_u32_e32 v210, v65, v16
	v_add_u32_e32 v211, v66, v16
	v_add_u32_e32 v212, v67, v16
	v_add_u32_e32 v213, v69, v16
	v_add_u32_e32 v214, v23, v16
	v_add_u32_e32 v215, v27, v16
	v_add_u32_e32 v216, v29, v16
	v_add_u32_e32 v217, v32, v16
	v_add_u32_e32 v218, v34, v16
	v_add_u32_e32 v219, v19, v16
	v_add_u32_e32 v220, v38, v16
	v_add_u32_e32 v221, v42, v16
	v_add_u32_e32 v222, v45, v16
	v_add_u32_e32 v223, v70, v16
	v_add_u32_e32 v224, v37, v16
	v_add_u32_e32 v225, v41, v16
	v_add_u32_e32 v226, v44, v16
	v_add_u32_e32 v227, v47, v16
	v_add_u32_e32 v228, v17, v16
	v_add_u32_e32 v229, v61, v16
	v_add_u32_e32 v230, v64, v16
	v_add_u32_e32 v231, v26, v16
	v_add_u32_e32 v232, v31, v16
	v_add_u32_e32 v233, v68, v16
	v_mov_b64_e32 v[30:31], v[14:15]
	v_mov_b64_e32 v[46:47], v[14:15]
	v_mov_b64_e32 v[62:63], v[14:15]
	v_mov_b64_e32 v[78:79], v[14:15]
	s_mov_b32 s92, 2
	v_mov_b32_e32 v147, s2
	s_or_b32 s46, s1, 31
	v_lshlrev_b32_e32 v174, 1, v171
	v_lshlrev_b32_e32 v175, 1, v172
	v_lshlrev_b32_e32 v176, 1, v173
	s_sub_i32 s2, 0, s1
	s_sub_i32 s47, 32, s1
	s_sub_i32 s50, 64, s1
	v_mov_b32_e32 v234, 0xf149f2ca
	v_mov_b32_e32 v179, 0
	s_movk_i32 s51, 0x60
	s_mov_b32 s1, s87
	v_mov_b64_e32 v[28:29], v[12:13]
	v_mov_b64_e32 v[26:27], v[10:11]
	v_mov_b64_e32 v[24:25], v[8:9]
	v_mov_b64_e32 v[22:23], v[6:7]
	v_mov_b64_e32 v[20:21], v[4:5]
	v_mov_b64_e32 v[18:19], v[2:3]
	v_mov_b64_e32 v[16:17], v[0:1]
	v_mov_b64_e32 v[44:45], v[12:13]
	v_mov_b64_e32 v[42:43], v[10:11]
	v_mov_b64_e32 v[40:41], v[8:9]
	v_mov_b64_e32 v[38:39], v[6:7]
	v_mov_b64_e32 v[36:37], v[4:5]
	v_mov_b64_e32 v[34:35], v[2:3]
	v_mov_b64_e32 v[32:33], v[0:1]
	v_mov_b64_e32 v[60:61], v[12:13]
	v_mov_b64_e32 v[58:59], v[10:11]
	v_mov_b64_e32 v[56:57], v[8:9]
	v_mov_b64_e32 v[54:55], v[6:7]
	v_mov_b64_e32 v[52:53], v[4:5]
	v_mov_b64_e32 v[50:51], v[2:3]
	v_mov_b64_e32 v[48:49], v[0:1]
	v_mov_b64_e32 v[76:77], v[12:13]
	v_mov_b64_e32 v[74:75], v[10:11]
	v_mov_b64_e32 v[72:73], v[8:9]
	v_mov_b64_e32 v[70:71], v[6:7]
	v_mov_b64_e32 v[68:69], v[4:5]
	v_mov_b64_e32 v[66:67], v[2:3]
	v_mov_b64_e32 v[64:65], v[0:1]
	s_waitcnt vmcnt(0)
	s_cmp_ge_u32 s33, 0x100
	s_cbranch_scc0 .Lmy_prio_a2
	s_setprio 1

.LBB0_2463:
	v_sub_f32_e32 v0, v80, v234
	v_exp_f32_e32 v9, v0
	v_sub_f32_e32 v0, v81, v234
	v_exp_f32_e32 v10, v0
	v_sub_f32_e32 v0, v82, v234
	v_exp_f32_e32 v4, v0
	v_sub_f32_e32 v0, v83, v234
	v_exp_f32_e32 v0, v0
	v_add_f32_e32 v5, v9, v10
	v_pk_add_f32 v[2:3], v[4:5], v[0:1]
	s_nop 0
	v_pk_add_f32 v[6:7], v[2:3], v[2:3] op_sel_hi:[0,1]
	v_sub_f32_e32 v2, v84, v234
	v_exp_f32_e32 v13, v2
	v_sub_f32_e32 v2, v85, v234
	v_exp_f32_e32 v14, v2
	v_sub_f32_e32 v2, v86, v234
	v_exp_f32_e32 v8, v2
	v_sub_f32_e32 v2, v87, v234
	v_exp_f32_e32 v6, v2
	v_cvt_pk_bf16_f32 v2, v9, v10
	v_add_f32_e32 v9, v13, v14
	v_cvt_pk_bf16_f32 v3, v4, v0
	v_pk_add_f32 v[4:5], v[8:9], v[6:7]
	v_sub_f32_e32 v0, v88, v234
	v_pk_add_f32 v[10:11], v[4:5], v[4:5] op_sel_hi:[0,1]
	v_sub_f32_e32 v4, v89, v234
	v_exp_f32_e32 v9, v4
	v_sub_f32_e32 v4, v90, v234
	v_exp_f32_e32 v0, v0
	v_exp_f32_e32 v12, v4
	v_sub_f32_e32 v4, v91, v234
	v_exp_f32_e32 v10, v4
	v_cvt_pk_bf16_f32 v4, v13, v14
	v_add_f32_e32 v13, v0, v9
	v_cvt_pk_bf16_f32 v5, v8, v6
	v_pk_add_f32 v[6:7], v[12:13], v[10:11]
	s_nop 0
	v_pk_add_f32 v[14:15], v[6:7], v[6:7] op_sel_hi:[0,1]
	v_sub_f32_e32 v6, v92, v234
	v_exp_f32_e32 v89, v6
	v_sub_f32_e32 v6, v93, v234
	v_exp_f32_e32 v90, v6
	v_sub_f32_e32 v6, v94, v234
	v_exp_f32_e32 v88, v6
	v_sub_f32_e32 v6, v95, v234
	v_exp_f32_e32 v14, v6
	v_cvt_pk_bf16_f32 v6, v0, v9
	v_cvt_pk_bf16_f32 v7, v12, v10
	v_cvt_pk_bf16_f32 v8, v89, v90
	v_cvt_pk_bf16_f32 v9, v88, v14
	ds_read_b64_tr_b16 v[10:11], v213
	ds_read_b64_tr_b16 v[12:13], v214
	ds_read_b64_tr_b16 v[80:81], v215
	ds_read_b64_tr_b16 v[82:83], v216
	ds_read_b64_tr_b16 v[84:85], v217
	ds_read_b64_tr_b16 v[86:87], v218
	v_add_f32_e32 v89, v89, v90
	v_pk_add_f32 v[14:15], v[88:89], v[14:15]
	s_nop 0
	v_add_f32_e32 v0, v14, v15
	v_add_f32_e32 v179, v179, v0
	s_waitcnt lgkmcnt(4)
	v_mfma_f32_32x32x16_bf16 v[64:79], v[10:13], v[2:5], v[64:79]
	ds_read_b64_tr_b16 v[88:89], v229 offset:8192
	ds_read_b64_tr_b16 v[90:91], v219 offset:10240
	s_waitcnt lgkmcnt(4)
	v_mfma_f32_32x32x16_bf16 v[48:63], v[80:83], v[2:5], v[48:63]
	ds_read_b64_tr_b16 v[10:11], v220 offset:12288
	ds_read_b64_tr_b16 v[12:13], v230 offset:14336
	s_waitcnt lgkmcnt(4)
	v_mfma_f32_32x32x16_bf16 v[32:47], v[84:87], v[2:5], v[32:47]
	ds_read_b64_tr_b16 v[80:81], v221 offset:12288
	ds_read_b64_tr_b16 v[82:83], v231 offset:14336
	s_waitcnt lgkmcnt(4)
	v_mfma_f32_32x32x16_bf16 v[16:31], v[88:91], v[2:5], v[16:31]
	ds_read_b64_tr_b16 v[84:85], v222 offset:12288
	ds_read_b64_tr_b16 v[86:87], v232 offset:14336
	s_waitcnt lgkmcnt(4)
	v_mfma_f32_32x32x16_bf16 v[64:79], v[10:13], v[6:9], v[64:79]
	ds_read_b64_tr_b16 v[2:3], v223 offset:12288
	ds_read_b64_tr_b16 v[4:5], v233 offset:14336
	s_waitcnt lgkmcnt(4)
	v_mfma_f32_32x32x16_bf16 v[48:63], v[80:83], v[6:9], v[48:63]
	s_waitcnt lgkmcnt(2)
	v_mfma_f32_32x32x16_bf16 v[32:47], v[84:87], v[6:9], v[32:47]
	s_waitcnt lgkmcnt(0)
	v_mfma_f32_32x32x16_bf16 v[16:31], v[2:5], v[6:9], v[16:31]

.LBB0_2467:
	s_add_i32 s77, s2, s51
	s_add_i32 s4, s51, 0xffffffa0
	s_cmp_gt_i32 s4, s46
	v_add_u32_e32 v12, v151, v152
	v_add_u32_e32 v13, v151, v153
	v_add_u32_e32 v14, v151, v154
	v_add_u32_e32 v15, v151, v155
	v_add_u32_e32 v11, v151, v156
	v_add_u32_e32 v10, v151, v157
	v_add_u32_e32 v9, v151, v164
	v_add_u32_e32 v8, v151, v165
	v_add_u32_e32 v7, v151, v166
	v_add_u32_e32 v6, v151, v167
	v_add_u32_e32 v5, v151, v168
	v_add_u32_e32 v2, v151, v169
	s_cbranch_scc1 .LBB0_2478
	ds_read_b128 v[80:83], v12
	ds_read_b128 v[236:239], v13
	ds_read_b128 v[240:243], v14
	ds_read_b128 v[244:247], v15
	s_waitcnt lgkmcnt(0)
	v_mfma_f32_32x32x16_bf16 v[80:95], v[80:83], v[140:143], 0
	ds_read_b128 v[248:251], v11
	v_mfma_f32_32x32x16_bf16 v[80:95], v[236:239], v[136:139], v[80:95]
	ds_read_b128 v[192:195], v10
	v_mfma_f32_32x32x16_bf16 v[80:95], v[240:243], v[132:135], v[80:95]
	ds_read_b128 v[236:239], v9
	v_mfma_f32_32x32x16_bf16 v[80:95], v[244:247], v[128:131], v[80:95]
	ds_read_b128 v[240:243], v8
	s_waitcnt lgkmcnt(0)
	v_mfma_f32_32x32x16_bf16 v[80:95], v[248:251], v[124:127], v[80:95]
	ds_read_b128 v[244:247], v7
	v_mfma_f32_32x32x16_bf16 v[80:95], v[192:195], v[120:123], v[80:95]
	ds_read_b128 v[248:251], v6
	v_mfma_f32_32x32x16_bf16 v[80:95], v[236:239], v[116:119], v[80:95]
	ds_read_b128 v[192:195], v5
	v_mfma_f32_32x32x16_bf16 v[80:95], v[240:243], v[112:115], v[80:95]
	ds_read_b128 v[236:239], v2
	s_waitcnt lgkmcnt(0)
	v_mfma_f32_32x32x16_bf16 v[80:95], v[244:247], v[108:111], v[80:95]
	v_mfma_f32_32x32x16_bf16 v[80:95], v[248:251], v[104:107], v[80:95]
	v_mfma_f32_32x32x16_bf16 v[80:95], v[192:195], v[100:103], v[80:95]
	v_mfma_f32_32x32x16_bf16 v[80:95], v[236:239], v[96:99], v[80:95]
	s_cmpk_lg_i32 s77, 0x60
	s_cbranch_scc1 .LBB0_2470
	s_nop 8
	v_cndmask_b32_e64 v0, v80, v161, s[8:9]
	v_cndmask_b32_e64 v81, v161, v81, s[12:13]
	v_cndmask_b32_e64 v80, v0, v80, s[12:13]
	v_cndmask_b32_e64 v82, v82, v161, s[14:15]
	v_cndmask_b32_e64 v83, v83, v161, s[16:17]
	v_cndmask_b32_e64 v84, v84, v161, s[18:19]
	v_cndmask_b32_e64 v85, v85, v161, s[20:21]
	v_cndmask_b32_e64 v86, v86, v161, s[22:23]
	v_cndmask_b32_e64 v87, v87, v161, s[24:25]
	v_cndmask_b32_e64 v88, v88, v161, s[26:27]
	v_cndmask_b32_e64 v89, v89, v161, s[28:29]
	v_cndmask_b32_e64 v90, v90, v161, s[30:31]
	v_cndmask_b32_e64 v91, v91, v161, s[34:35]
	v_cndmask_b32_e64 v92, v92, v161, s[36:37]
	v_cndmask_b32_e64 v93, v93, v161, s[38:39]
	v_cndmask_b32_e64 v94, v94, v161, s[40:41]
	v_cndmask_b32_e64 v95, v95, v161, s[42:43]

.LBB0_2472:
	v_sub_f32_e32 v0, v80, v234
	v_exp_f32_e32 v194, v0
	v_sub_f32_e32 v0, v81, v234
	v_exp_f32_e32 v195, v0
	v_sub_f32_e32 v0, v82, v234
	v_exp_f32_e32 v82, v0
	v_sub_f32_e32 v0, v83, v234
	v_exp_f32_e32 v0, v0
	v_add_f32_e32 v83, v194, v195
	v_pk_add_f32 v[80:81], v[82:83], v[0:1]
	s_nop 0
	v_pk_add_f32 v[192:193], v[80:81], v[80:81] op_sel_hi:[0,1]
	v_sub_f32_e32 v80, v84, v234
	v_exp_f32_e32 v236, v80
	v_sub_f32_e32 v80, v85, v234
	v_exp_f32_e32 v237, v80
	v_sub_f32_e32 v80, v86, v234
	v_exp_f32_e32 v84, v80
	v_sub_f32_e32 v80, v87, v234
	v_exp_f32_e32 v192, v80
	v_add_f32_e32 v85, v236, v237
	v_cvt_pk_bf16_f32 v80, v194, v195
	v_cvt_pk_bf16_f32 v81, v82, v0
	v_pk_add_f32 v[82:83], v[84:85], v[192:193]
	v_sub_f32_e32 v0, v88, v234
	v_pk_add_f32 v[86:87], v[82:83], v[82:83] op_sel_hi:[0,1]
	v_sub_f32_e32 v82, v89, v234
	v_exp_f32_e32 v193, v82
	v_sub_f32_e32 v82, v90, v234
	v_exp_f32_e32 v0, v0
	v_exp_f32_e32 v88, v82
	v_sub_f32_e32 v82, v91, v234
	v_exp_f32_e32 v86, v82
	v_add_f32_e32 v89, v0, v193
	v_cvt_pk_bf16_f32 v82, v236, v237
	v_cvt_pk_bf16_f32 v83, v84, v192
	v_pk_add_f32 v[84:85], v[88:89], v[86:87]
	s_nop 0
	v_pk_add_f32 v[236:237], v[84:85], v[84:85] op_sel_hi:[0,1]
	v_sub_f32_e32 v84, v92, v234
	v_exp_f32_e32 v239, v84
	v_sub_f32_e32 v84, v93, v234
	v_exp_f32_e32 v240, v84
	v_sub_f32_e32 v84, v94, v234
	v_exp_f32_e32 v238, v84
	v_sub_f32_e32 v84, v95, v234
	v_exp_f32_e32 v236, v84
	v_cvt_pk_bf16_f32 v84, v0, v193
	v_cvt_pk_bf16_f32 v85, v88, v86
	v_cvt_pk_bf16_f32 v86, v239, v240
	v_cvt_pk_bf16_f32 v87, v238, v236
	s_waitcnt vmcnt(0)
	ds_read_b64_tr_b16 v[88:89], v180 offset:49152
	ds_read_b64_tr_b16 v[90:91], v181 offset:49152
	ds_read_b64_tr_b16 v[92:93], v182 offset:49152
	ds_read_b64_tr_b16 v[94:95], v183 offset:49152
	ds_read_b64_tr_b16 v[192:193], v184 offset:49152
	ds_read_b64_tr_b16 v[194:195], v185 offset:49152
	v_add_f32_e32 v239, v239, v240
	v_pk_add_f32 v[236:237], v[238:239], v[236:237]
	s_nop 0
	v_add_f32_e32 v0, v236, v237
	v_add_f32_e32 v179, v179, v0
	s_waitcnt lgkmcnt(4)
	v_mfma_f32_32x32x16_bf16 v[64:79], v[88:91], v[80:83], v[64:79]
	ds_read_b64_tr_b16 v[236:237], v224 offset:49152
	ds_read_b64_tr_b16 v[238:239], v186 offset:49152
	s_waitcnt lgkmcnt(4)
	v_mfma_f32_32x32x16_bf16 v[48:63], v[92:95], v[80:83], v[48:63]
	ds_read_b64_tr_b16 v[88:89], v187 offset:49152
	ds_read_b64_tr_b16 v[90:91], v225 offset:55296
	s_waitcnt lgkmcnt(4)
	v_mfma_f32_32x32x16_bf16 v[32:47], v[192:195], v[80:83], v[32:47]
	ds_read_b64_tr_b16 v[92:93], v188 offset:49152
	ds_read_b64_tr_b16 v[94:95], v226 offset:55296
	s_waitcnt lgkmcnt(4)
	v_mfma_f32_32x32x16_bf16 v[16:31], v[236:239], v[80:83], v[16:31]
	ds_read_b64_tr_b16 v[192:193], v189 offset:49152
	ds_read_b64_tr_b16 v[194:195], v227 offset:55296
	s_waitcnt lgkmcnt(4)
	v_mfma_f32_32x32x16_bf16 v[64:79], v[88:91], v[84:87], v[64:79]
	ds_read_b64_tr_b16 v[80:81], v190 offset:49152
	ds_read_b64_tr_b16 v[82:83], v228 offset:55296
	s_waitcnt lgkmcnt(4)
	v_mfma_f32_32x32x16_bf16 v[48:63], v[92:95], v[84:87], v[48:63]
	s_waitcnt lgkmcnt(2)
	v_mfma_f32_32x32x16_bf16 v[32:47], v[192:195], v[84:87], v[32:47]
	s_waitcnt lgkmcnt(0)
	v_mfma_f32_32x32x16_bf16 v[16:31], v[80:83], v[84:87], v[16:31]
	s_sub_i32 s4, s51, 64
	s_cmp_gt_i32 s4, s46
	s_cbranch_scc1 .LBB0_2478
	v_add_u32_e32 v0, v170, v152
	v_add_u32_e32 v84, v170, v153
	ds_read_b128 v[80:83], v0
	ds_read_b128 v[192:195], v84
	v_add_u32_e32 v0, v170, v154
	v_add_u32_e32 v84, v170, v155
	ds_read_b128 v[236:239], v0
	ds_read_b128 v[240:243], v84
	s_add_i32 s4, s47, s51
	s_waitcnt lgkmcnt(3)
	v_mfma_f32_32x32x16_bf16 v[80:95], v[80:83], v[140:143], 0
	v_add_u32_e32 v0, v170, v156
	ds_read_b128 v[244:247], v0
	s_waitcnt lgkmcnt(3)
	v_mfma_f32_32x32x16_bf16 v[80:95], v[192:195], v[136:139], v[80:95]
	v_add_u32_e32 v0, v170, v157
	ds_read_b128 v[248:251], v0
	s_waitcnt lgkmcnt(3)
	v_mfma_f32_32x32x16_bf16 v[80:95], v[236:239], v[132:135], v[80:95]
	v_add_u32_e32 v0, v170, v164
	ds_read_b128 v[192:195], v0
	s_waitcnt lgkmcnt(3)
	v_mfma_f32_32x32x16_bf16 v[80:95], v[240:243], v[128:131], v[80:95]
	v_add_u32_e32 v0, v170, v165
	ds_read_b128 v[236:239], v0
	s_waitcnt lgkmcnt(3)
	v_mfma_f32_32x32x16_bf16 v[80:95], v[244:247], v[124:127], v[80:95]
	v_add_u32_e32 v0, v170, v166
	ds_read_b128 v[240:243], v0
	s_waitcnt lgkmcnt(3)
	v_mfma_f32_32x32x16_bf16 v[80:95], v[248:251], v[120:123], v[80:95]
	v_add_u32_e32 v0, v170, v167
	ds_read_b128 v[244:247], v0
	s_waitcnt lgkmcnt(3)
	v_mfma_f32_32x32x16_bf16 v[80:95], v[192:195], v[116:119], v[80:95]
	v_add_u32_e32 v0, v170, v168
	ds_read_b128 v[248:251], v0
	s_waitcnt lgkmcnt(3)
	v_mfma_f32_32x32x16_bf16 v[80:95], v[236:239], v[112:115], v[80:95]
	v_add_u32_e32 v0, v170, v169
	ds_read_b128 v[192:195], v0
	s_waitcnt lgkmcnt(3)
	v_mfma_f32_32x32x16_bf16 v[80:95], v[240:243], v[108:111], v[80:95]
	s_waitcnt lgkmcnt(2)
	v_mfma_f32_32x32x16_bf16 v[80:95], v[244:247], v[104:107], v[80:95]
	s_waitcnt lgkmcnt(1)
	v_mfma_f32_32x32x16_bf16 v[80:95], v[248:251], v[100:103], v[80:95]
	s_waitcnt lgkmcnt(0)
	v_mfma_f32_32x32x16_bf16 v[80:95], v[192:195], v[96:99], v[80:95]
	s_cmpk_lg_i32 s4, 0x60
	s_cbranch_scc1 .LBB0_2475
	s_nop 8
	v_cndmask_b32_e64 v0, v80, v161, s[8:9]
	v_cndmask_b32_e64 v81, v161, v81, s[12:13]
	v_cndmask_b32_e64 v80, v0, v80, s[12:13]
	v_cndmask_b32_e64 v82, v82, v161, s[14:15]
	v_cndmask_b32_e64 v83, v83, v161, s[16:17]
	v_cndmask_b32_e64 v84, v84, v161, s[18:19]
	v_cndmask_b32_e64 v85, v85, v161, s[20:21]
	v_cndmask_b32_e64 v86, v86, v161, s[22:23]
	v_cndmask_b32_e64 v87, v87, v161, s[24:25]
	v_cndmask_b32_e64 v88, v88, v161, s[26:27]
	v_cndmask_b32_e64 v89, v89, v161, s[28:29]
	v_cndmask_b32_e64 v90, v90, v161, s[30:31]
	v_cndmask_b32_e64 v91, v91, v161, s[34:35]
	v_cndmask_b32_e64 v92, v92, v161, s[36:37]
	v_cndmask_b32_e64 v93, v93, v161, s[38:39]
	v_cndmask_b32_e64 v94, v94, v161, s[40:41]
	v_cndmask_b32_e64 v95, v95, v161, s[42:43]

.LBB0_2477:
	v_sub_f32_e32 v0, v80, v234
	v_exp_f32_e32 v194, v0
	v_sub_f32_e32 v0, v81, v234
	v_exp_f32_e32 v195, v0
	v_sub_f32_e32 v0, v82, v234
	v_exp_f32_e32 v82, v0
	v_sub_f32_e32 v0, v83, v234
	v_exp_f32_e32 v0, v0
	v_add_f32_e32 v83, v194, v195
	v_pk_add_f32 v[80:81], v[82:83], v[0:1]
	s_nop 0
	v_pk_add_f32 v[192:193], v[80:81], v[80:81] op_sel_hi:[0,1]
	v_sub_f32_e32 v80, v84, v234
	v_exp_f32_e32 v236, v80
	v_sub_f32_e32 v80, v85, v234
	v_exp_f32_e32 v237, v80
	v_sub_f32_e32 v80, v86, v234
	v_exp_f32_e32 v84, v80
	v_sub_f32_e32 v80, v87, v234
	v_exp_f32_e32 v192, v80
	v_add_f32_e32 v85, v236, v237
	v_cvt_pk_bf16_f32 v80, v194, v195
	v_cvt_pk_bf16_f32 v81, v82, v0
	v_pk_add_f32 v[82:83], v[84:85], v[192:193]
	v_sub_f32_e32 v0, v88, v234
	v_pk_add_f32 v[86:87], v[82:83], v[82:83] op_sel_hi:[0,1]
	v_sub_f32_e32 v82, v89, v234
	v_exp_f32_e32 v193, v82
	v_sub_f32_e32 v82, v90, v234
	v_exp_f32_e32 v0, v0
	v_exp_f32_e32 v88, v82
	v_sub_f32_e32 v82, v91, v234
	v_exp_f32_e32 v86, v82
	v_add_f32_e32 v89, v0, v193
	v_cvt_pk_bf16_f32 v82, v236, v237
	v_cvt_pk_bf16_f32 v83, v84, v192
	v_pk_add_f32 v[84:85], v[88:89], v[86:87]
	s_nop 0
	v_pk_add_f32 v[236:237], v[84:85], v[84:85] op_sel_hi:[0,1]
	v_sub_f32_e32 v84, v92, v234
	v_exp_f32_e32 v239, v84
	v_sub_f32_e32 v84, v93, v234
	v_exp_f32_e32 v240, v84
	v_sub_f32_e32 v84, v94, v234
	v_exp_f32_e32 v238, v84
	v_sub_f32_e32 v84, v95, v234
	v_exp_f32_e32 v236, v84
	v_cvt_pk_bf16_f32 v84, v0, v193
	v_cvt_pk_bf16_f32 v85, v88, v86
	v_cvt_pk_bf16_f32 v86, v239, v240
	v_cvt_pk_bf16_f32 v87, v238, v236
	ds_read_b64_tr_b16 v[88:89], v191 offset:49152
	ds_read_b64_tr_b16 v[90:91], v235 offset:49152
	ds_read_b64_tr_b16 v[92:93], v252 offset:49152
	ds_read_b64_tr_b16 v[94:95], v253 offset:49152
	ds_read_b64_tr_b16 v[192:193], v254 offset:49152
	ds_read_b64_tr_b16 v[194:195], v196 offset:49152
	v_add_f32_e32 v239, v239, v240
	v_pk_add_f32 v[236:237], v[238:239], v[236:237]
	s_nop 0
	v_add_f32_e32 v0, v236, v237
	v_add_f32_e32 v179, v179, v0
	s_waitcnt lgkmcnt(4)
	v_mfma_f32_32x32x16_bf16 v[64:79], v[88:91], v[80:83], v[64:79]
	ds_read_b64_tr_b16 v[236:237], v224 offset:57344
	ds_read_b64_tr_b16 v[238:239], v197 offset:59392
	s_waitcnt lgkmcnt(4)
	v_mfma_f32_32x32x16_bf16 v[48:63], v[92:95], v[80:83], v[48:63]
	ds_read_b64_tr_b16 v[88:89], v198 offset:61440
	ds_read_b64_tr_b16 v[90:91], v225 offset:63488
	s_waitcnt lgkmcnt(4)
	v_mfma_f32_32x32x16_bf16 v[32:47], v[192:195], v[80:83], v[32:47]
	ds_read_b64_tr_b16 v[92:93], v199 offset:61440
	ds_read_b64_tr_b16 v[94:95], v226 offset:63488
	s_waitcnt lgkmcnt(4)
	v_mfma_f32_32x32x16_bf16 v[16:31], v[236:239], v[80:83], v[16:31]
	ds_read_b64_tr_b16 v[192:193], v200 offset:61440
	ds_read_b64_tr_b16 v[194:195], v227 offset:63488
	s_waitcnt lgkmcnt(4)
	v_mfma_f32_32x32x16_bf16 v[64:79], v[88:91], v[84:87], v[64:79]
	ds_read_b64_tr_b16 v[80:81], v201 offset:61440
	ds_read_b64_tr_b16 v[82:83], v228 offset:63488
	s_waitcnt lgkmcnt(4)
	v_mfma_f32_32x32x16_bf16 v[48:63], v[92:95], v[84:87], v[48:63]
	s_waitcnt lgkmcnt(2)
	v_mfma_f32_32x32x16_bf16 v[32:47], v[192:195], v[84:87], v[32:47]
	s_waitcnt lgkmcnt(0)
	v_mfma_f32_32x32x16_bf16 v[16:31], v[80:83], v[84:87], v[16:31]

.LBB0_2480:
	s_sub_i32 s84, s51, 32
	s_cmp_gt_i32 s84, s46
	s_cbranch_scc1 .LBB0_2464
	ds_read_b128 v[80:83], v12 offset:24576
	ds_read_b128 v[192:195], v13 offset:24576
	ds_read_b128 v[236:239], v14 offset:24576
	ds_read_b128 v[12:15], v15 offset:24576
	s_add_i32 s84, s50, s51
	s_waitcnt lgkmcnt(0)
	v_mfma_f32_32x32x16_bf16 v[80:95], v[80:83], v[140:143], 0
	ds_read_b128 v[240:243], v11 offset:24576
	v_mfma_f32_32x32x16_bf16 v[80:95], v[192:195], v[136:139], v[80:95]
	ds_read_b128 v[244:247], v10 offset:24576
	v_mfma_f32_32x32x16_bf16 v[80:95], v[236:239], v[132:135], v[80:95]
	ds_read_b128 v[192:195], v9 offset:24576
	v_mfma_f32_32x32x16_bf16 v[80:95], v[12:15], v[128:131], v[80:95]
	ds_read_b128 v[8:11], v8 offset:24576
	s_waitcnt lgkmcnt(0)
	v_mfma_f32_32x32x16_bf16 v[80:95], v[240:243], v[124:127], v[80:95]
	ds_read_b128 v[12:15], v7 offset:24576
	v_mfma_f32_32x32x16_bf16 v[80:95], v[244:247], v[120:123], v[80:95]
	ds_read_b128 v[236:239], v6 offset:24576
	v_mfma_f32_32x32x16_bf16 v[80:95], v[192:195], v[116:119], v[80:95]
	ds_read_b128 v[4:7], v5 offset:24576
	v_mfma_f32_32x32x16_bf16 v[80:95], v[8:11], v[112:115], v[80:95]
	ds_read_b128 v[192:195], v2 offset:24576
	s_waitcnt lgkmcnt(0)
	v_mfma_f32_32x32x16_bf16 v[80:95], v[12:15], v[108:111], v[80:95]
	v_mfma_f32_32x32x16_bf16 v[80:95], v[236:239], v[104:107], v[80:95]
	v_mfma_f32_32x32x16_bf16 v[80:95], v[4:7], v[100:103], v[80:95]
	v_mfma_f32_32x32x16_bf16 v[80:95], v[192:195], v[96:99], v[80:95]
	s_cmpk_lg_i32 s84, 0x60
	s_cbranch_scc1 .LBB0_2483
	s_nop 8
	v_cndmask_b32_e64 v0, v80, v161, s[8:9]
	v_cndmask_b32_e64 v81, v161, v81, s[12:13]
	v_cndmask_b32_e64 v80, v0, v80, s[12:13]
	v_cndmask_b32_e64 v82, v82, v161, s[14:15]
	v_cndmask_b32_e64 v83, v83, v161, s[16:17]
	v_cndmask_b32_e64 v84, v84, v161, s[18:19]
	v_cndmask_b32_e64 v85, v85, v161, s[20:21]
	v_cndmask_b32_e64 v86, v86, v161, s[22:23]
	v_cndmask_b32_e64 v87, v87, v161, s[24:25]
	v_cndmask_b32_e64 v88, v88, v161, s[26:27]
	v_cndmask_b32_e64 v89, v89, v161, s[28:29]
	v_cndmask_b32_e64 v90, v90, v161, s[30:31]
	v_cndmask_b32_e64 v91, v91, v161, s[34:35]
	v_cndmask_b32_e64 v92, v92, v161, s[36:37]
	v_cndmask_b32_e64 v93, v93, v161, s[38:39]
	v_cndmask_b32_e64 v94, v94, v161, s[40:41]
	v_cndmask_b32_e64 v95, v95, v161, s[42:43]

.LBB0_2485:
	v_sub_f32_e32 v0, v80, v234
	v_exp_f32_e32 v9, v0
	v_sub_f32_e32 v0, v81, v234
	v_exp_f32_e32 v10, v0
	v_sub_f32_e32 v0, v82, v234
	v_exp_f32_e32 v4, v0
	v_sub_f32_e32 v0, v83, v234
	v_exp_f32_e32 v0, v0
	v_add_f32_e32 v5, v9, v10
	v_pk_add_f32 v[2:3], v[4:5], v[0:1]
	s_nop 0
	v_pk_add_f32 v[6:7], v[2:3], v[2:3] op_sel_hi:[0,1]
	v_sub_f32_e32 v2, v84, v234
	v_exp_f32_e32 v13, v2
	v_sub_f32_e32 v2, v85, v234
	v_exp_f32_e32 v14, v2
	v_sub_f32_e32 v2, v86, v234
	v_exp_f32_e32 v8, v2
	v_sub_f32_e32 v2, v87, v234
	v_exp_f32_e32 v6, v2
	v_cvt_pk_bf16_f32 v2, v9, v10
	v_add_f32_e32 v9, v13, v14
	v_cvt_pk_bf16_f32 v3, v4, v0
	v_pk_add_f32 v[4:5], v[8:9], v[6:7]
	v_sub_f32_e32 v0, v88, v234
	v_pk_add_f32 v[10:11], v[4:5], v[4:5] op_sel_hi:[0,1]
	v_sub_f32_e32 v4, v89, v234
	v_exp_f32_e32 v9, v4
	v_sub_f32_e32 v4, v90, v234
	v_exp_f32_e32 v0, v0
	v_exp_f32_e32 v12, v4
	v_sub_f32_e32 v4, v91, v234
	v_exp_f32_e32 v10, v4
	v_cvt_pk_bf16_f32 v4, v13, v14
	v_add_f32_e32 v13, v0, v9
	v_cvt_pk_bf16_f32 v5, v8, v6
	v_pk_add_f32 v[6:7], v[12:13], v[10:11]
	s_nop 0
	v_pk_add_f32 v[14:15], v[6:7], v[6:7] op_sel_hi:[0,1]
	v_sub_f32_e32 v6, v92, v234
	v_exp_f32_e32 v89, v6
	v_sub_f32_e32 v6, v93, v234
	v_exp_f32_e32 v90, v6
	v_sub_f32_e32 v6, v94, v234
	v_exp_f32_e32 v88, v6
	v_sub_f32_e32 v6, v95, v234
	v_exp_f32_e32 v14, v6
	v_cvt_pk_bf16_f32 v6, v0, v9
	v_cvt_pk_bf16_f32 v7, v12, v10
	v_cvt_pk_bf16_f32 v8, v89, v90
	v_cvt_pk_bf16_f32 v9, v88, v14
	s_waitcnt vmcnt(0)
	ds_read_b64_tr_b16 v[10:11], v202
	ds_read_b64_tr_b16 v[12:13], v203
	ds_read_b64_tr_b16 v[80:81], v204
	ds_read_b64_tr_b16 v[82:83], v205
	ds_read_b64_tr_b16 v[84:85], v206
	ds_read_b64_tr_b16 v[86:87], v207
	v_add_f32_e32 v89, v89, v90
	v_pk_add_f32 v[14:15], v[88:89], v[14:15]
	s_nop 0
	v_add_f32_e32 v0, v14, v15
	v_add_f32_e32 v179, v179, v0
	s_waitcnt lgkmcnt(4)
	v_mfma_f32_32x32x16_bf16 v[64:79], v[10:13], v[2:5], v[64:79]
	ds_read_b64_tr_b16 v[88:89], v229
	ds_read_b64_tr_b16 v[90:91], v208
	s_waitcnt lgkmcnt(4)
	v_mfma_f32_32x32x16_bf16 v[48:63], v[80:83], v[2:5], v[48:63]
	ds_read_b64_tr_b16 v[10:11], v209
	ds_read_b64_tr_b16 v[12:13], v230 offset:6144
	s_waitcnt lgkmcnt(4)
	v_mfma_f32_32x32x16_bf16 v[32:47], v[84:87], v[2:5], v[32:47]
	ds_read_b64_tr_b16 v[80:81], v210
	ds_read_b64_tr_b16 v[82:83], v231 offset:6144
	s_waitcnt lgkmcnt(4)
	v_mfma_f32_32x32x16_bf16 v[16:31], v[88:91], v[2:5], v[16:31]
	ds_read_b64_tr_b16 v[84:85], v211
	ds_read_b64_tr_b16 v[86:87], v232 offset:6144
	s_waitcnt lgkmcnt(4)
	v_mfma_f32_32x32x16_bf16 v[64:79], v[10:13], v[6:9], v[64:79]
	ds_read_b64_tr_b16 v[2:3], v212
	ds_read_b64_tr_b16 v[4:5], v233 offset:6144
	s_waitcnt lgkmcnt(4)
	v_mfma_f32_32x32x16_bf16 v[48:63], v[80:83], v[6:9], v[48:63]
	s_waitcnt lgkmcnt(2)
	v_mfma_f32_32x32x16_bf16 v[32:47], v[84:87], v[6:9], v[32:47]
	s_waitcnt lgkmcnt(0)
	v_mfma_f32_32x32x16_bf16 v[16:31], v[2:5], v[6:9], v[16:31]
	s_cmp_gt_i32 s51, s46
	s_cbranch_scc1 .LBB0_2464
	v_add_u32_e32 v0, v170, v152
	v_add_u32_e32 v6, v170, v153
	ds_read_b128 v[2:5], v0 offset:24576
	ds_read_b128 v[6:9], v6 offset:24576
	v_add_u32_e32 v0, v170, v154
	v_add_u32_e32 v14, v170, v155
	ds_read_b128 v[10:13], v0 offset:24576
	ds_read_b128 v[192:195], v14 offset:24576
	s_waitcnt lgkmcnt(3)
	v_mfma_f32_32x32x16_bf16 v[80:95], v[2:5], v[140:143], 0
	v_add_u32_e32 v0, v170, v156
	ds_read_b128 v[236:239], v0 offset:24576
	s_waitcnt lgkmcnt(3)
	v_mfma_f32_32x32x16_bf16 v[80:95], v[6:9], v[136:139], v[80:95]
	v_add_u32_e32 v0, v170, v157
	ds_read_b128 v[2:5], v0 offset:24576
	s_waitcnt lgkmcnt(3)
	v_mfma_f32_32x32x16_bf16 v[80:95], v[10:13], v[132:135], v[80:95]
	v_add_u32_e32 v0, v170, v164
	ds_read_b128 v[6:9], v0 offset:24576
	s_waitcnt lgkmcnt(3)
	v_mfma_f32_32x32x16_bf16 v[80:95], v[192:195], v[128:131], v[80:95]
	v_add_u32_e32 v0, v170, v165
	ds_read_b128 v[10:13], v0 offset:24576
	s_waitcnt lgkmcnt(3)
	v_mfma_f32_32x32x16_bf16 v[80:95], v[236:239], v[124:127], v[80:95]
	v_add_u32_e32 v0, v170, v166
	ds_read_b128 v[192:195], v0 offset:24576
	s_waitcnt lgkmcnt(3)
	v_mfma_f32_32x32x16_bf16 v[80:95], v[2:5], v[120:123], v[80:95]
	v_add_u32_e32 v0, v170, v167
	ds_read_b128 v[236:239], v0 offset:24576
	s_waitcnt lgkmcnt(3)
	v_mfma_f32_32x32x16_bf16 v[80:95], v[6:9], v[116:119], v[80:95]
	v_add_u32_e32 v0, v170, v168
	ds_read_b128 v[2:5], v0 offset:24576
	s_waitcnt lgkmcnt(3)
	v_mfma_f32_32x32x16_bf16 v[80:95], v[10:13], v[112:115], v[80:95]
	v_add_u32_e32 v0, v170, v169
	ds_read_b128 v[6:9], v0 offset:24576
	s_waitcnt lgkmcnt(3)
	v_mfma_f32_32x32x16_bf16 v[80:95], v[192:195], v[108:111], v[80:95]
	s_waitcnt lgkmcnt(2)
	v_mfma_f32_32x32x16_bf16 v[80:95], v[236:239], v[104:107], v[80:95]
	s_waitcnt lgkmcnt(1)
	v_mfma_f32_32x32x16_bf16 v[80:95], v[2:5], v[100:103], v[80:95]
	s_waitcnt lgkmcnt(0)
	v_mfma_f32_32x32x16_bf16 v[80:95], v[6:9], v[96:99], v[80:95]
	s_cmp_lg_u32 s77, 0
	s_cbranch_scc1 .LBB0_2488
	s_nop 8
	v_cndmask_b32_e64 v0, v80, v161, s[8:9]
	v_cndmask_b32_e64 v81, v161, v81, s[12:13]
	v_cndmask_b32_e64 v80, v0, v80, s[12:13]
	v_cndmask_b32_e64 v82, v82, v161, s[14:15]
	v_cndmask_b32_e64 v83, v83, v161, s[16:17]
	v_cndmask_b32_e64 v84, v84, v161, s[18:19]
	v_cndmask_b32_e64 v85, v85, v161, s[20:21]
	v_cndmask_b32_e64 v86, v86, v161, s[22:23]
	v_cndmask_b32_e64 v87, v87, v161, s[24:25]
	v_cndmask_b32_e64 v88, v88, v161, s[26:27]
	v_cndmask_b32_e64 v89, v89, v161, s[28:29]
	v_cndmask_b32_e64 v90, v90, v161, s[30:31]
	v_cndmask_b32_e64 v91, v91, v161, s[34:35]
	v_cndmask_b32_e64 v92, v92, v161, s[36:37]
	v_cndmask_b32_e64 v93, v93, v161, s[38:39]
	v_cndmask_b32_e64 v94, v94, v161, s[40:41]
	v_cndmask_b32_e64 v95, v95, v161, s[42:43]

.LBB0_3760:
	s_setprio 0
	ds_bpermute_b32 v0, v155, v178
	v_lshlrev_b64 v[2:3], 12, v[146:147]
	s_lshl_b32 s4, s90, 7
	v_lshl_add_u64 v[2:3], s[42:43], 0, v[2:3]
	s_ashr_i32 s5, s4, 31
	s_waitcnt lgkmcnt(0)
	v_add_f32_e32 v0, v178, v0
	v_div_scale_f32 v4, s[8:9], v0, v0, 1.0
	v_rcp_f32_e32 v5, v4
	v_div_scale_f32 v6, vcc, 1.0, v0, 1.0
	v_lshl_add_u64 v[2:3], s[4:5], 1, v[2:3]
	v_fma_f32 v7, -v4, v5, 1.0
	v_fmac_f32_e32 v5, v7, v5
	v_mul_f32_e32 v7, v6, v5
	v_fma_f32 v8, -v4, v7, v6
	v_fmac_f32_e32 v7, v8, v5
	v_fma_f32 v4, -v4, v7, v6
	v_div_fmas_f32 v4, v4, v5, v7
	v_div_fixup_f32 v8, v4, v0, 1.0
	v_lshlrev_b32_e32 v0, 1, v144
	v_lshl_add_u64 v[6:7], v[2:3], 0, v[0:1]
	v_mul_f32_e32 v0, v64, v8
	v_mul_f32_e32 v2, v65, v8
	v_cvt_pk_bf16_f32 v2, v0, v2
	v_mul_f32_e32 v0, v66, v8
	v_mul_f32_e32 v3, v67, v8
	v_cvt_pk_bf16_f32 v3, v0, v3
	v_mul_f32_e32 v0, v68, v8
	v_mul_f32_e32 v4, v69, v8
	v_mul_f32_e32 v5, v71, v8
	v_cvt_pk_bf16_f32 v4, v0, v4
	v_mul_f32_e32 v0, v70, v8
	v_cvt_pk_bf16_f32 v5, v0, v5
	v_permlane32_swap_b32_e32 v2, v4
	v_permlane32_swap_b32_e32 v3, v5
	global_store_dwordx4 v[6:7], v[2:5], off
	v_mul_f32_e32 v0, v72, v8
	s_add_i32 s87, s87, 1
	v_mul_f32_e32 v2, v73, v8
	v_cvt_pk_bf16_f32 v2, v0, v2
	v_mul_f32_e32 v0, v74, v8
	v_mul_f32_e32 v3, v75, v8
	v_cvt_pk_bf16_f32 v3, v0, v3
	v_mul_f32_e32 v0, v76, v8
	v_mul_f32_e32 v4, v77, v8
	v_mul_f32_e32 v5, v79, v8
	v_cvt_pk_bf16_f32 v4, v0, v4
	v_mul_f32_e32 v0, v78, v8
	v_cvt_pk_bf16_f32 v5, v0, v5
	v_permlane32_swap_b32_e32 v2, v4
	v_permlane32_swap_b32_e32 v3, v5
	global_store_dwordx4 v[6:7], v[2:5], off offset:32
	v_mul_f32_e32 v0, v48, v8
	s_add_i32 s86, s86, 0x80000
	v_mul_f32_e32 v2, v49, v8
	v_cvt_pk_bf16_f32 v2, v0, v2
	v_mul_f32_e32 v0, v50, v8
	v_mul_f32_e32 v3, v51, v8
	v_cvt_pk_bf16_f32 v3, v0, v3
	v_mul_f32_e32 v0, v52, v8
	v_mul_f32_e32 v4, v53, v8
	v_mul_f32_e32 v5, v55, v8
	v_cvt_pk_bf16_f32 v4, v0, v4
	v_mul_f32_e32 v0, v54, v8
	v_cvt_pk_bf16_f32 v5, v0, v5
	v_permlane32_swap_b32_e32 v2, v4
	v_permlane32_swap_b32_e32 v3, v5
	global_store_dwordx4 v[6:7], v[2:5], off offset:64
	v_mul_f32_e32 v0, v56, v8
	s_cmp_lg_u32 s87, s63
	v_mul_f32_e32 v2, v57, v8
	v_cvt_pk_bf16_f32 v2, v0, v2
	v_mul_f32_e32 v0, v58, v8
	v_mul_f32_e32 v3, v59, v8
	v_cvt_pk_bf16_f32 v3, v0, v3
	v_mul_f32_e32 v0, v60, v8
	v_mul_f32_e32 v4, v61, v8
	v_mul_f32_e32 v5, v63, v8
	v_cvt_pk_bf16_f32 v4, v0, v4
	v_mul_f32_e32 v0, v62, v8
	v_cvt_pk_bf16_f32 v5, v0, v5
	v_permlane32_swap_b32_e32 v2, v4
	v_permlane32_swap_b32_e32 v3, v5
	global_store_dwordx4 v[6:7], v[2:5], off offset:96
	v_mul_f32_e32 v0, v32, v8
	s_nop 0
	v_mul_f32_e32 v2, v33, v8
	v_cvt_pk_bf16_f32 v2, v0, v2
	v_mul_f32_e32 v0, v34, v8
	v_mul_f32_e32 v3, v35, v8
	v_cvt_pk_bf16_f32 v3, v0, v3
	v_mul_f32_e32 v0, v36, v8
	v_mul_f32_e32 v4, v37, v8
	v_mul_f32_e32 v5, v39, v8
	v_cvt_pk_bf16_f32 v4, v0, v4
	v_mul_f32_e32 v0, v38, v8
	v_cvt_pk_bf16_f32 v5, v0, v5
	v_permlane32_swap_b32_e32 v2, v4
	v_permlane32_swap_b32_e32 v3, v5
	global_store_dwordx4 v[6:7], v[2:5], off offset:128
	v_mul_f32_e32 v0, v40, v8
	s_nop 0
	v_mul_f32_e32 v2, v41, v8
	v_cvt_pk_bf16_f32 v2, v0, v2
	v_mul_f32_e32 v0, v42, v8
	v_mul_f32_e32 v3, v43, v8
	v_cvt_pk_bf16_f32 v3, v0, v3
	v_mul_f32_e32 v0, v44, v8
	v_mul_f32_e32 v4, v45, v8
	v_mul_f32_e32 v5, v47, v8
	v_cvt_pk_bf16_f32 v4, v0, v4
	v_mul_f32_e32 v0, v46, v8
	v_cvt_pk_bf16_f32 v5, v0, v5
	v_permlane32_swap_b32_e32 v2, v4
	v_permlane32_swap_b32_e32 v3, v5
	global_store_dwordx4 v[6:7], v[2:5], off offset:160
	v_mul_f32_e32 v0, v16, v8
	s_nop 0
	v_mul_f32_e32 v2, v17, v8
	v_cvt_pk_bf16_f32 v2, v0, v2
	v_mul_f32_e32 v0, v18, v8
	v_mul_f32_e32 v3, v19, v8
	v_cvt_pk_bf16_f32 v3, v0, v3
	v_mul_f32_e32 v0, v20, v8
	v_mul_f32_e32 v4, v21, v8
	v_mul_f32_e32 v5, v23, v8
	v_cvt_pk_bf16_f32 v4, v0, v4
	v_mul_f32_e32 v0, v22, v8
	v_cvt_pk_bf16_f32 v5, v0, v5
	v_permlane32_swap_b32_e32 v2, v4
	v_permlane32_swap_b32_e32 v3, v5
	global_store_dwordx4 v[6:7], v[2:5], off offset:192
	v_mul_f32_e32 v0, v24, v8
	s_nop 0
	v_mul_f32_e32 v2, v25, v8
	v_cvt_pk_bf16_f32 v2, v0, v2
	v_mul_f32_e32 v0, v26, v8
	v_mul_f32_e32 v3, v27, v8
	v_cvt_pk_bf16_f32 v3, v0, v3
	v_mul_f32_e32 v0, v28, v8
	v_mul_f32_e32 v4, v29, v8
	v_mul_f32_e32 v5, v31, v8
	v_cvt_pk_bf16_f32 v4, v0, v4
	v_mul_f32_e32 v0, v30, v8
	v_cvt_pk_bf16_f32 v5, v0, v5
	v_permlane32_swap_b32_e32 v2, v4
	v_permlane32_swap_b32_e32 v3, v5
	global_store_dwordx4 v[6:7], v[2:5], off offset:224
	s_cbranch_scc0 .LBB0_3802
.LBB0_3761:
	v_mov_b32_e32 v0, v1
	s_movk_i32 s2, 0xffc0
	v_mbcnt_lo_u32_b32 v0, -1, v0
	v_mbcnt_hi_u32_b32 v0, -1, v0
	v_add_u32_e32 v4, s33, v0
	s_nop 0
	v_readfirstlane_b32 s1, v4
	s_nop 1
	v_mov_b32_e32 v0, s1
	v_bfi_b32 v0, s2, v0, v4
	v_mul_hi_i32 v2, v0, s97
	v_lshrrev_b32_e32 v3, 31, v2
	v_ashrrev_i32_e32 v2, 2, v2
	v_add_u32_e32 v2, v2, v3
	v_lshlrev_b32_e32 v3, 1, v2
	v_mad_u64_u32 v[6:7], s[4:5], v2, s56, v[0:1]
	v_and_b32_e32 v3, 4, v3
	v_bfe_u32 v5, v2, 2, 2
	v_bitop3_b32 v5, v3, v6, v5 bitop3:0x36
	v_cmp_lt_i32_e32 vcc, 15, v5
	s_and_saveexec_b64 s[4:5], vcc
	s_xor_b64 s[4:5], exec, s[4:5]
	v_mul_lo_u32 v2, v2, s57
	v_add_u32_e32 v6, s78, v2
	s_or_saveexec_b64 s[4:5], s[4:5]
	s_add_i32 s90, s87, s74
	s_lshl_b32 s2, s90, 19
	s_add_i32 s2, s2, s76
	s_add_i32 s8, s2, 0x639ff300
	v_mov_b32_e32 v3, 1
	s_xor_b64 exec, exec, s[4:5]
	v_lshl_add_u32 v6, v2, 8, s8
	v_mov_b32_e32 v3, 0
	s_or_b64 exec, exec, s[4:5]
	v_add_u32_e32 v2, 0x200, v0
	v_mul_hi_i32 v7, v2, s97
	v_lshrrev_b32_e32 v8, 31, v7
	v_ashrrev_i32_e32 v7, 2, v7
	v_add_u32_e32 v9, v7, v8
	v_lshlrev_b32_e32 v7, 1, v9
	v_mad_u64_u32 v[10:11], s[4:5], v9, s56, v[2:3]
	v_and_b32_e32 v7, 4, v7
	v_bfe_u32 v8, v9, 2, 2
	v_bitop3_b32 v7, v7, v10, v8 bitop3:0x36
	v_cmp_lt_i32_e32 vcc, 15, v7
	s_and_saveexec_b64 s[4:5], vcc
	s_xor_b64 s[4:5], exec, s[4:5]
	v_mul_lo_u32 v8, v9, s57
	v_add_u32_e32 v8, s78, v8
	v_or_b32_e32 v3, 2, v3
	s_andn2_saveexec_b64 s[4:5], s[4:5]
	v_lshl_add_u32 v8, v9, 8, s8
	s_or_b64 exec, exec, s[4:5]
	v_add_u32_e32 v10, 0x400, v0
	v_mul_hi_i32 v9, v10, s97
	v_lshrrev_b32_e32 v11, 31, v9
	v_ashrrev_i32_e32 v9, 2, v9
	v_add_u32_e32 v11, v9, v11
	v_lshlrev_b32_e32 v9, 1, v11
	v_mad_u64_u32 v[12:13], s[4:5], v11, s56, v[10:11]
	v_and_b32_e32 v9, 4, v9
	v_bfe_u32 v10, v11, 2, 2
	v_bitop3_b32 v9, v9, v12, v10 bitop3:0x36
	v_cmp_lt_i32_e32 vcc, 15, v9
	s_and_saveexec_b64 s[4:5], vcc
	s_xor_b64 s[4:5], exec, s[4:5]
	v_mul_lo_u32 v10, v11, s57
	v_add_u32_e32 v10, s78, v10
	v_or_b32_e32 v3, 4, v3
	s_andn2_saveexec_b64 s[4:5], s[4:5]
	v_lshl_add_u32 v10, v11, 8, s8
	s_or_b64 exec, exec, s[4:5]
	v_ashrrev_i32_e32 v0, 4, v0
	v_lshl_add_u32 v152, v7, 4, v8
	v_lshlrev_b32_e32 v7, 2, v0
	v_lshl_add_u32 v153, v5, 4, v6
	v_and_b32_e32 v6, 15, v4
	v_and_b32_e32 v7, 12, v7
	v_bfe_u32 v8, v0, 2, 2
	v_bitop3_b32 v7, v7, v6, v8 bitop3:0x36
	v_ashrrev_i32_e32 v2, 4, v2
	v_lshl_add_u32 v154, v9, 4, v10
	v_lshlrev_b32_e32 v9, 4, v7
	v_lshlrev_b32_e32 v7, 2, v2
	s_bitcmp0_b32 s87, 0
	v_and_b32_e32 v7, 12, v7
	v_bfe_u32 v10, v2, 2, 2
	s_cselect_b32 s4, s72, s75
	s_ashr_i32 s5, s1, 6
	s_add_i32 s2, s2, 0x679ff300
	v_lshlrev_b32_e32 v8, 8, v0
	v_bitop3_b32 v6, v7, v6, v10 bitop3:0x36
	v_lshlrev_b32_e32 v2, 8, v2
	v_add_u32_e32 v0, s2, v8
	v_lshlrev_b32_e32 v10, 4, v6
	v_add_u32_e32 v6, s2, v2
	s_lshl_b32 s2, s5, 10
	s_add_i32 s65, s2, 0
	s_waitcnt lgkmcnt(0)
	s_barrier
	s_mov_b32 m0, s65
	s_add_i32 s52, s65, 0x2000
	s_lshl_b32 s1, s5, 5
	s_lshl_b32 s64, s4, 2
	s_lshl_b32 s4, s4, 8
	global_load_lds_dwordx4 v153, s[82:83]
	s_mov_b32 m0, s52
	s_add_i32 s53, s65, 0x4000
	s_add_i32 s1, s1, s4
	global_load_lds_dwordx4 v152, s[82:83]
	s_mov_b32 m0, s53
	s_add_i32 s60, s65, 0xc000
	s_add_i32 s64, s64, 4
	v_or_b32_e32 v0, v9, v0
	global_load_lds_dwordx4 v154, s[82:83]
	s_mov_b32 m0, s60
	s_add_i32 s61, s65, 0xe000
	s_ashr_i32 s2, s1, 31
	v_and_b32_e32 v5, 31, v4
	v_or_b32_e32 v6, v10, v6
	global_load_lds_dwordx4 v0, s[82:83]
	s_mov_b32 m0, s61
	s_add_u32 s4, s1, s77
	global_load_lds_dwordx4 v6, s[82:83]
	v_or_b32_e32 v146, s4, v5
	v_mov_b64_e32 v[6:7], s[44:45]
	s_movk_i32 s4, 0x1800
	v_mad_u64_u32 v[6:7], s[4:5], v146, s4, v[6:7]
	s_addc_u32 s2, s2, 0
	v_lshrrev_b32_e32 v0, 2, v4
	s_mul_i32 s4, s90, 0xc0
	v_and_b32_e32 v144, 8, v0
	v_mad_i32_i24 v7, s2, v145, v7
	s_ashr_i32 s5, s4, 31
	v_lshl_add_u64 v[6:7], s[4:5], 1, v[6:7]
	v_lshlrev_b32_e32 v0, 1, v144
	v_lshl_add_u64 v[6:7], v[6:7], 0, v[0:1]
	global_load_dwordx4 v[96:99], v[6:7], off offset:352
	global_load_dwordx4 v[100:103], v[6:7], off offset:320
	global_load_dwordx4 v[104:107], v[6:7], off offset:288
	global_load_dwordx4 v[108:111], v[6:7], off offset:256
	global_load_dwordx4 v[112:115], v[6:7], off offset:224
	global_load_dwordx4 v[116:119], v[6:7], off offset:192
	global_load_dwordx4 v[120:123], v[6:7], off offset:160
	global_load_dwordx4 v[124:127], v[6:7], off offset:128
	global_load_dwordx4 v[128:131], v[6:7], off offset:96
	global_load_dwordx4 v[132:135], v[6:7], off offset:64
	global_load_dwordx4 v[136:139], v[6:7], off offset:32
	global_load_dwordx4 v[140:143], v[6:7], off
	v_and_b32_e32 v11, 63, v4
	v_lshlrev_b32_e32 v7, 1, v11
	v_lshrrev_b32_e32 v0, 5, v11
	v_bfe_u32 v6, v4, 2, 2
	v_and_b32_e32 v7, 4, v7
	v_or_b32_e32 v17, 2, v0
	v_bitop3_b32 v20, v7, v0, v6 bitop3:0x36
	v_lshlrev_b32_e32 v157, 4, v20
	v_bitop3_b32 v20, v7, v17, v6 bitop3:0x36
	v_lshlrev_b32_e32 v158, 4, v20
	v_or_b32_e32 v20, 4, v0
	v_bitop3_b32 v20, v7, v20, v6 bitop3:0x36
	v_lshlrev_b32_e32 v159, 4, v20
	v_or_b32_e32 v20, 6, v0
	v_bitop3_b32 v20, v7, v20, v6 bitop3:0x36
	v_lshlrev_b32_e32 v160, 4, v20
	v_or_b32_e32 v20, 8, v0
	v_bitop3_b32 v20, v7, v20, v6 bitop3:0x36
	v_lshlrev_b32_e32 v161, 4, v20
	v_or_b32_e32 v20, 10, v0
	v_bitop3_b32 v20, v7, v20, v6 bitop3:0x36
	v_lshlrev_b32_e32 v162, 4, v20
	v_or_b32_e32 v20, 12, v0
	v_bitop3_b32 v20, v7, v20, v6 bitop3:0x36
	v_lshlrev_b32_e32 v163, 4, v20
	v_or_b32_e32 v20, 14, v0
	v_bitop3_b32 v20, v7, v20, v6 bitop3:0x36
	v_lshlrev_b32_e32 v164, 4, v20
	v_or_b32_e32 v20, 16, v0
	v_bitop3_b32 v20, v7, v20, v6 bitop3:0x36
	v_lshlrev_b32_e32 v165, 4, v20
	v_or_b32_e32 v20, 18, v0
	v_bitop3_b32 v20, v7, v20, v6 bitop3:0x36
	v_lshlrev_b32_e32 v166, 4, v20
	v_or_b32_e32 v20, 20, v0
	v_bitop3_b32 v20, v7, v20, v6 bitop3:0x36
	v_lshlrev_b32_e32 v167, 4, v20
	v_or_b32_e32 v20, 22, v0
	v_lshlrev_b32_e32 v12, 2, v0
	v_bitop3_b32 v7, v7, v20, v6 bitop3:0x36
	v_lshlrev_b32_e32 v168, 4, v7
	v_or_b32_e32 v7, 2, v12
	v_cmp_gt_u32_e64 s[12:13], v7, v5
	v_or_b32_e32 v7, 3, v12
	v_cmp_gt_u32_e64 s[14:15], v7, v5
	v_or_b32_e32 v7, 9, v12
	v_cmp_gt_u32_e64 s[18:19], v7, v5
	v_or_b32_e32 v7, 10, v12
	v_cmp_gt_u32_e64 s[20:21], v7, v5
	v_or_b32_e32 v7, 11, v12
	v_cmp_gt_u32_e64 s[22:23], v7, v5
	v_or_b32_e32 v7, 17, v12
	v_cmp_gt_u32_e64 s[26:27], v7, v5
	v_or_b32_e32 v7, 18, v12
	v_cmp_gt_u32_e64 s[28:29], v7, v5
	v_or_b32_e32 v7, 19, v12
	v_cmp_gt_u32_e64 s[30:31], v7, v5
	v_or_b32_e32 v7, 24, v12
	v_cmp_gt_u32_e64 s[34:35], v7, v5
	v_or_b32_e32 v7, 25, v12
	v_lshlrev_b32_e32 v13, 2, v11
	v_cmp_gt_u32_e64 s[36:37], v7, v5
	v_or_b32_e32 v7, 26, v12
	v_xor_b32_e32 v155, 0x80, v13
	v_lshrrev_b32_e32 v13, 3, v4
	v_bfe_u32 v14, v4, 1, 1
	v_or_b32_e32 v15, 16, v12
	v_or_b32_e32 v18, 8, v12
	v_cmp_gt_u32_e64 s[38:39], v7, v5
	v_or_b32_e32 v7, 27, v12
	v_and_b32_e32 v4, 12, v4
	v_and_or_b32 v13, v13, 2, v14
	v_lshlrev_b32_e32 v14, 3, v11
	v_mad_u32_u24 v156, v5, s54, 0
	v_cmp_gt_u32_e64 s[8:9], v12, v5
	v_cmp_lt_u32_e64 s[10:11], v12, v5
	v_cmp_gt_u32_e64 s[16:17], v18, v5
	v_cmp_gt_u32_e64 s[24:25], v15, v5
	v_cmp_gt_u32_e64 s[40:41], v7, v5
	v_or_b32_e32 v5, v12, v6
	v_or_b32_e32 v7, v0, v4
	v_and_b32_e32 v16, 8, v14
	v_lshlrev_b32_e32 v14, 2, v6
	v_lshrrev_b32_e32 v19, 2, v18
	v_lshlrev_b32_e32 v5, 8, v5
	v_or_b32_e32 v26, 4, v13
	v_bitop3_b32 v27, v13, v7, 4 bitop3:0x36
	v_or_b32_e32 v31, 8, v13
	v_bitop3_b32 v32, v13, v7, 8 bitop3:0x36
	v_or_b32_e32 v36, 12, v13
	v_bitop3_b32 v7, v13, v7, 12 bitop3:0x36
	v_or_b32_e32 v15, v15, v6
	v_bitop3_b32 v4, v0, v13, v4 bitop3:0x36
	v_add_u32_e32 v20, 0, v5
	v_or_b32_e32 v22, v18, v6
	v_bitop3_b32 v23, v19, v13, v14 bitop3:0x36
	v_bitop3_b32 v29, v19, v26, v14 bitop3:0x36
	v_bitop3_b32 v34, v19, v31, v14 bitop3:0x36
	v_lshlrev_b32_e32 v7, 4, v7
	v_bitop3_b32 v19, v19, v36, v14 bitop3:0x36
	v_bitop3_b32 v38, v14, v13, v0 bitop3:0x36
	v_lshlrev_b32_e32 v15, 8, v15
	v_bitop3_b32 v13, v14, v13, v17 bitop3:0x36
	v_bitop3_b32 v42, v14, v26, v0 bitop3:0x36
	v_bitop3_b32 v26, v14, v26, v17 bitop3:0x36
	v_bitop3_b32 v45, v14, v31, v0 bitop3:0x36
	v_bitop3_b32 v31, v14, v31, v17 bitop3:0x36
	v_bitop3_b32 v0, v14, v36, v0 bitop3:0x36
	v_bitop3_b32 v14, v14, v36, v17 bitop3:0x36
	v_or_b32_e32 v11, 32, v11
	v_or_b32_e32 v6, 32, v6
	v_add_u32_e32 v5, s55, v5
	v_lshlrev_b32_e32 v4, 4, v4
	v_lshlrev_b32_e32 v27, 4, v27
	v_lshlrev_b32_e32 v32, 4, v32
	v_add_u32_e32 v37, v20, v7
	v_lshlrev_b32_e32 v19, 4, v19
	v_add_u32_e32 v39, 0, v15
	v_lshlrev_b32_e32 v38, 4, v38
	v_lshlrev_b32_e32 v13, 4, v13
	v_lshlrev_b32_e32 v42, 4, v42
	v_lshlrev_b32_e32 v26, 4, v26
	v_lshlrev_b32_e32 v45, 4, v45
	v_lshlrev_b32_e32 v31, 4, v31
	v_lshlrev_b32_e32 v0, 4, v0
	v_lshlrev_b32_e32 v14, 4, v14
	v_mad_u32_u24 v169, v11, s54, 0
	v_or_b32_e32 v11, v6, v12
	v_add_u32_e32 v61, v5, v7
	v_add_u32_e32 v7, s55, v15
	v_add_u32_e32 v21, v20, v4
	v_add_u32_e32 v28, v20, v27
	v_add_u32_e32 v33, v20, v32
	v_add_u32_e32 v40, v39, v38
	v_add_u32_e32 v41, v20, v13
	v_add_u32_e32 v43, v39, v42
	v_add_u32_e32 v44, v20, v26
	v_add_u32_e32 v46, v39, v45
	v_add_u32_e32 v47, v20, v31
	v_add_u32_e32 v39, v39, v0
	v_add_u32_e32 v17, v20, v14
	v_lshlrev_b32_e32 v11, 8, v11
	v_or_b32_e32 v6, v18, v6
	v_add_u32_e32 v52, v20, v19
	v_add_u32_e32 v53, v20, v38
	v_add_u32_e32 v54, v20, v42
	v_add_u32_e32 v55, v20, v45
	v_add_u32_e32 v20, v20, v0
	v_add_u32_e32 v67, v7, v0
	v_add_u32_e32 v70, v5, v0
	v_and_b32_e32 v0, 1, v3
	v_lshlrev_b32_e32 v22, 8, v22
	v_add_u32_e32 v12, 0, v11
	v_lshlrev_b32_e32 v6, 8, v6
	v_add_u32_e32 v63, v7, v38
	v_add_u32_e32 v65, v7, v42
	v_add_u32_e32 v66, v7, v45
	v_add_u32_e32 v7, s55, v11
	v_cmp_eq_u32_e32 vcc, 0, v0
	v_and_b32_e32 v0, 2, v3
	v_add_u32_e32 v24, 0, v22
	v_lshlrev_b32_e32 v23, 4, v23
	v_lshlrev_b32_e32 v29, 4, v29
	v_lshlrev_b32_e32 v34, 4, v34
	v_add_u32_e32 v36, v12, v4
	v_add_u32_e32 v18, 0, v6
	v_add_u32_e32 v49, v12, v27
	v_add_u32_e32 v51, v12, v32
	v_add_u32_e32 v56, v5, v4
	v_add_u32_e32 v12, s55, v22
	v_add_u32_e32 v69, v7, v4
	v_add_u32_e32 v4, s55, v6
	v_cndmask_b32_e32 v170, v148, v149, vcc
	v_cmp_eq_u32_e32 vcc, 0, v0
	v_and_b32_e32 v0, 4, v3
	v_add_u32_e32 v25, v24, v23
	v_add_u32_e32 v30, v24, v29
	v_add_u32_e32 v35, v24, v34
	v_add_u32_e32 v24, v24, v19
	v_add_u32_e32 v48, v18, v23
	v_add_u32_e32 v50, v18, v29
	v_add_u32_e32 v18, v18, v34
	v_add_u32_e32 v22, v12, v23
	v_add_u32_e32 v57, v5, v27
	v_add_u32_e32 v58, v12, v29
	v_add_u32_e32 v59, v5, v32
	v_add_u32_e32 v60, v12, v34
	v_add_u32_e32 v62, v12, v19
	v_add_u32_e32 v64, v5, v13
	v_add_u32_e32 v26, v5, v26
	v_add_u32_e32 v31, v5, v31
	v_add_u32_e32 v68, v5, v14
	v_add_u32_e32 v23, v4, v23
	v_add_u32_e32 v27, v7, v27
	v_add_u32_e32 v29, v4, v29
	v_add_u32_e32 v32, v7, v32
	v_add_u32_e32 v34, v4, v34
	v_add_u32_e32 v19, v5, v19
	v_add_u32_e32 v38, v5, v38
	v_add_u32_e32 v42, v5, v42
	v_add_u32_e32 v45, v5, v45
	v_cndmask_b32_e32 v171, v148, v149, vcc
	v_cmp_eq_u32_e32 vcc, 0, v0
	v_mov_b32_e32 v14, v1
	v_mov_b32_e32 v15, v1
	v_cndmask_b32_e32 v172, v148, v149, vcc
	v_or_b32_e32 v176, v2, v10
	v_or_b32_e32 v177, v8, v9
	v_mov_b32_e32 v0, v1
	v_mov_b32_e32 v2, v1
	v_mov_b32_e32 v3, v1
	v_mov_b32_e32 v4, v1
	v_mov_b32_e32 v5, v1
	v_mov_b32_e32 v6, v1
	v_mov_b32_e32 v7, v1
	v_mov_b32_e32 v8, v1
	v_mov_b32_e32 v9, v1
	v_mov_b32_e32 v10, v1
	v_mov_b32_e32 v11, v1
	v_mov_b32_e32 v12, v1
	v_mov_b32_e32 v13, v1
	v_add_u32_e32 v179, v21, v16
	v_add_u32_e32 v180, v25, v16
	v_add_u32_e32 v181, v28, v16
	v_add_u32_e32 v182, v30, v16
	v_add_u32_e32 v183, v33, v16
	v_add_u32_e32 v184, v35, v16
	v_add_u32_e32 v185, v24, v16
	v_add_u32_e32 v186, v40, v16
	v_add_u32_e32 v187, v43, v16
	v_add_u32_e32 v188, v46, v16
	v_add_u32_e32 v189, v39, v16
	v_add_u32_e32 v190, v36, v16
	v_add_u32_e32 v191, v48, v16
	v_add_u32_e32 v192, v49, v16
	v_add_u32_e32 v193, v50, v16
	v_add_u32_e32 v194, v51, v16
	v_add_u32_e32 v195, v18, v16
	v_add_u32_e32 v196, v52, v16
	v_add_u32_e32 v197, v53, v16
	v_add_u32_e32 v198, v54, v16
	v_add_u32_e32 v199, v55, v16
	v_add_u32_e32 v200, v20, v16
	v_add_u32_e32 v201, v56, v16
	v_add_u32_e32 v202, v22, v16
	v_add_u32_e32 v203, v57, v16
	v_add_u32_e32 v204, v58, v16
	v_add_u32_e32 v205, v59, v16
	v_add_u32_e32 v206, v60, v16
	v_add_u32_e32 v207, v62, v16
	v_add_u32_e32 v208, v63, v16
	v_add_u32_e32 v209, v65, v16
	v_add_u32_e32 v210, v66, v16
	v_add_u32_e32 v211, v67, v16
	v_add_u32_e32 v212, v69, v16
	v_add_u32_e32 v213, v23, v16
	v_add_u32_e32 v214, v27, v16
	v_add_u32_e32 v215, v29, v16
	v_add_u32_e32 v216, v32, v16
	v_add_u32_e32 v217, v34, v16
	v_add_u32_e32 v218, v19, v16
	v_add_u32_e32 v219, v38, v16
	v_add_u32_e32 v220, v42, v16
	v_add_u32_e32 v221, v45, v16
	v_add_u32_e32 v222, v70, v16
	v_add_u32_e32 v223, v37, v16
	v_add_u32_e32 v224, v41, v16
	v_add_u32_e32 v225, v44, v16
	v_add_u32_e32 v226, v47, v16
	v_add_u32_e32 v227, v17, v16
	s_waitcnt vmcnt(0)
	v_add_u32_e32 v228, v61, v16
	v_add_u32_e32 v229, v64, v16
	v_add_u32_e32 v230, v26, v16
	v_add_u32_e32 v231, v31, v16
	v_add_u32_e32 v232, v68, v16
	v_mov_b64_e32 v[30:31], v[14:15]
	v_mov_b64_e32 v[46:47], v[14:15]
	v_mov_b64_e32 v[62:63], v[14:15]
	v_mov_b64_e32 v[78:79], v[14:15]
	s_mov_b32 s91, 2
	v_mov_b32_e32 v147, s2
	s_or_b32 s88, s1, 31
	v_lshlrev_b32_e32 v173, 1, v170
	v_lshlrev_b32_e32 v174, 1, v171
	v_lshlrev_b32_e32 v175, 1, v172
	s_sub_i32 s2, 0, s1
	s_sub_i32 s89, 32, s1
	s_sub_i32 s66, 64, s1
	v_mov_b32_e32 v233, 0xf149f2ca
	v_mov_b32_e32 v178, 0
	s_movk_i32 s67, 0x60
	s_mov_b32 s1, s86
	v_mov_b64_e32 v[28:29], v[12:13]
	v_mov_b64_e32 v[26:27], v[10:11]
	v_mov_b64_e32 v[24:25], v[8:9]
	v_mov_b64_e32 v[22:23], v[6:7]
	v_mov_b64_e32 v[20:21], v[4:5]
	v_mov_b64_e32 v[18:19], v[2:3]
	v_mov_b64_e32 v[16:17], v[0:1]
	v_mov_b64_e32 v[44:45], v[12:13]
	v_mov_b64_e32 v[42:43], v[10:11]
	v_mov_b64_e32 v[40:41], v[8:9]
	v_mov_b64_e32 v[38:39], v[6:7]
	v_mov_b64_e32 v[36:37], v[4:5]
	v_mov_b64_e32 v[34:35], v[2:3]
	v_mov_b64_e32 v[32:33], v[0:1]
	v_mov_b64_e32 v[60:61], v[12:13]
	v_mov_b64_e32 v[58:59], v[10:11]
	v_mov_b64_e32 v[56:57], v[8:9]
	v_mov_b64_e32 v[54:55], v[6:7]
	v_mov_b64_e32 v[52:53], v[4:5]
	v_mov_b64_e32 v[50:51], v[2:3]
	v_mov_b64_e32 v[48:49], v[0:1]
	v_mov_b64_e32 v[76:77], v[12:13]
	v_mov_b64_e32 v[74:75], v[10:11]
	v_mov_b64_e32 v[72:73], v[8:9]
	v_mov_b64_e32 v[70:71], v[6:7]
	v_mov_b64_e32 v[68:69], v[4:5]
	v_mov_b64_e32 v[66:67], v[2:3]
	v_mov_b64_e32 v[64:65], v[0:1]
	s_cmp_ge_u32 s33, 0x100
	s_cbranch_scc0 .Lmy_prio_a3
	s_setprio 1

.LBB0_3774:
	v_sub_f32_e32 v0, v80, v233
	v_exp_f32_e32 v9, v0
	v_sub_f32_e32 v0, v81, v233
	v_exp_f32_e32 v10, v0
	v_sub_f32_e32 v0, v82, v233
	v_exp_f32_e32 v4, v0
	v_sub_f32_e32 v0, v83, v233
	v_exp_f32_e32 v0, v0
	v_add_f32_e32 v5, v9, v10
	v_pk_add_f32 v[2:3], v[4:5], v[0:1]
	s_nop 0
	v_pk_add_f32 v[6:7], v[2:3], v[2:3] op_sel_hi:[0,1]
	v_sub_f32_e32 v2, v84, v233
	v_exp_f32_e32 v13, v2
	v_sub_f32_e32 v2, v85, v233
	v_exp_f32_e32 v14, v2
	v_sub_f32_e32 v2, v86, v233
	v_exp_f32_e32 v8, v2
	v_sub_f32_e32 v2, v87, v233
	v_exp_f32_e32 v6, v2
	v_cvt_pk_bf16_f32 v2, v9, v10
	v_add_f32_e32 v9, v13, v14
	v_cvt_pk_bf16_f32 v3, v4, v0
	v_pk_add_f32 v[4:5], v[8:9], v[6:7]
	v_sub_f32_e32 v0, v88, v233
	v_pk_add_f32 v[10:11], v[4:5], v[4:5] op_sel_hi:[0,1]
	v_sub_f32_e32 v4, v89, v233
	v_exp_f32_e32 v9, v4
	v_sub_f32_e32 v4, v90, v233
	v_exp_f32_e32 v0, v0
	v_exp_f32_e32 v12, v4
	v_sub_f32_e32 v4, v91, v233
	v_exp_f32_e32 v10, v4
	v_cvt_pk_bf16_f32 v4, v13, v14
	v_add_f32_e32 v13, v0, v9
	v_cvt_pk_bf16_f32 v5, v8, v6
	v_pk_add_f32 v[6:7], v[12:13], v[10:11]
	s_nop 0
	v_pk_add_f32 v[14:15], v[6:7], v[6:7] op_sel_hi:[0,1]
	v_sub_f32_e32 v6, v92, v233
	v_exp_f32_e32 v89, v6
	v_sub_f32_e32 v6, v93, v233
	v_exp_f32_e32 v90, v6
	v_sub_f32_e32 v6, v94, v233
	v_exp_f32_e32 v88, v6
	v_sub_f32_e32 v6, v95, v233
	v_exp_f32_e32 v14, v6
	v_cvt_pk_bf16_f32 v6, v0, v9
	v_cvt_pk_bf16_f32 v7, v12, v10
	v_cvt_pk_bf16_f32 v8, v89, v90
	v_cvt_pk_bf16_f32 v9, v88, v14
	ds_read_b64_tr_b16 v[10:11], v212
	ds_read_b64_tr_b16 v[12:13], v213
	ds_read_b64_tr_b16 v[80:81], v214
	ds_read_b64_tr_b16 v[82:83], v215
	ds_read_b64_tr_b16 v[84:85], v216
	ds_read_b64_tr_b16 v[86:87], v217
	v_add_f32_e32 v89, v89, v90
	v_pk_add_f32 v[14:15], v[88:89], v[14:15]
	s_nop 0
	v_add_f32_e32 v0, v14, v15
	v_add_f32_e32 v178, v178, v0
	s_waitcnt lgkmcnt(4)
	v_mfma_f32_32x32x16_bf16 v[64:79], v[10:13], v[2:5], v[64:79]
	ds_read_b64_tr_b16 v[88:89], v228 offset:8192
	ds_read_b64_tr_b16 v[90:91], v218 offset:10240
	s_waitcnt lgkmcnt(4)
	v_mfma_f32_32x32x16_bf16 v[48:63], v[80:83], v[2:5], v[48:63]
	ds_read_b64_tr_b16 v[10:11], v219 offset:12288
	ds_read_b64_tr_b16 v[12:13], v229 offset:14336
	s_waitcnt lgkmcnt(4)
	v_mfma_f32_32x32x16_bf16 v[32:47], v[84:87], v[2:5], v[32:47]
	ds_read_b64_tr_b16 v[80:81], v220 offset:12288
	ds_read_b64_tr_b16 v[82:83], v230 offset:14336
	s_waitcnt lgkmcnt(4)
	v_mfma_f32_32x32x16_bf16 v[16:31], v[88:91], v[2:5], v[16:31]
	ds_read_b64_tr_b16 v[84:85], v221 offset:12288
	ds_read_b64_tr_b16 v[86:87], v231 offset:14336
	s_waitcnt lgkmcnt(4)
	v_mfma_f32_32x32x16_bf16 v[64:79], v[10:13], v[6:9], v[64:79]
	ds_read_b64_tr_b16 v[2:3], v222 offset:12288
	ds_read_b64_tr_b16 v[4:5], v232 offset:14336
	s_waitcnt lgkmcnt(4)
	v_mfma_f32_32x32x16_bf16 v[48:63], v[80:83], v[6:9], v[48:63]
	s_waitcnt lgkmcnt(2)
	v_mfma_f32_32x32x16_bf16 v[32:47], v[84:87], v[6:9], v[32:47]
	s_waitcnt lgkmcnt(0)
	v_mfma_f32_32x32x16_bf16 v[16:31], v[2:5], v[6:9], v[16:31]

.LBB0_3778:
	s_add_i32 s84, s2, s67
	s_add_i32 s4, s67, 0xffffffa0
	s_cmp_gt_i32 s4, s88
	v_add_u32_e32 v12, v156, v157
	v_add_u32_e32 v13, v156, v158
	v_add_u32_e32 v14, v156, v159
	v_add_u32_e32 v15, v156, v160
	v_add_u32_e32 v11, v156, v161
	v_add_u32_e32 v10, v156, v162
	v_add_u32_e32 v9, v156, v163
	v_add_u32_e32 v8, v156, v164
	v_add_u32_e32 v7, v156, v165
	v_add_u32_e32 v6, v156, v166
	v_add_u32_e32 v5, v156, v167
	v_add_u32_e32 v2, v156, v168
	s_cbranch_scc1 .LBB0_3789
	ds_read_b128 v[80:83], v12
	ds_read_b128 v[234:237], v13
	ds_read_b128 v[238:241], v14
	ds_read_b128 v[242:245], v15
	s_waitcnt lgkmcnt(0)
	v_mfma_f32_32x32x16_bf16 v[80:95], v[80:83], v[140:143], 0
	ds_read_b128 v[246:249], v11
	v_mfma_f32_32x32x16_bf16 v[80:95], v[234:237], v[136:139], v[80:95]
	ds_read_b128 v[250:253], v10
	v_mfma_f32_32x32x16_bf16 v[80:95], v[238:241], v[132:135], v[80:95]
	ds_read_b128 v[234:237], v9
	v_mfma_f32_32x32x16_bf16 v[80:95], v[242:245], v[128:131], v[80:95]
	ds_read_b128 v[238:241], v8
	s_waitcnt lgkmcnt(0)
	v_mfma_f32_32x32x16_bf16 v[80:95], v[246:249], v[124:127], v[80:95]
	ds_read_b128 v[242:245], v7
	v_mfma_f32_32x32x16_bf16 v[80:95], v[250:253], v[120:123], v[80:95]
	ds_read_b128 v[246:249], v6
	v_mfma_f32_32x32x16_bf16 v[80:95], v[234:237], v[116:119], v[80:95]
	ds_read_b128 v[250:253], v5
	v_mfma_f32_32x32x16_bf16 v[80:95], v[238:241], v[112:115], v[80:95]
	ds_read_b128 v[234:237], v2
	s_waitcnt lgkmcnt(0)
	v_mfma_f32_32x32x16_bf16 v[80:95], v[242:245], v[108:111], v[80:95]
	v_mfma_f32_32x32x16_bf16 v[80:95], v[246:249], v[104:107], v[80:95]
	v_mfma_f32_32x32x16_bf16 v[80:95], v[250:253], v[100:103], v[80:95]
	v_mfma_f32_32x32x16_bf16 v[80:95], v[234:237], v[96:99], v[80:95]
	s_cmpk_lg_i32 s84, 0x60
	s_cbranch_scc1 .LBB0_3781
	s_nop 8
	v_cndmask_b32_e64 v0, v80, v150, s[8:9]
	v_cndmask_b32_e64 v81, v150, v81, s[10:11]
	v_cndmask_b32_e64 v80, v0, v80, s[10:11]
	v_cndmask_b32_e64 v82, v82, v150, s[12:13]
	v_cndmask_b32_e64 v83, v83, v150, s[14:15]
	v_cndmask_b32_e64 v84, v84, v150, s[16:17]
	v_cndmask_b32_e64 v85, v85, v150, s[18:19]
	v_cndmask_b32_e64 v86, v86, v150, s[20:21]
	v_cndmask_b32_e64 v87, v87, v150, s[22:23]
	v_cndmask_b32_e64 v88, v88, v150, s[24:25]
	v_cndmask_b32_e64 v89, v89, v150, s[26:27]
	v_cndmask_b32_e64 v90, v90, v150, s[28:29]
	v_cndmask_b32_e64 v91, v91, v150, s[30:31]
	v_cndmask_b32_e64 v92, v92, v150, s[34:35]
	v_cndmask_b32_e64 v93, v93, v150, s[36:37]
	v_cndmask_b32_e64 v94, v94, v150, s[38:39]
	v_cndmask_b32_e64 v95, v95, v150, s[40:41]

.LBB0_3783:
	v_sub_f32_e32 v0, v80, v233
	v_exp_f32_e32 v236, v0
	v_sub_f32_e32 v0, v81, v233
	v_exp_f32_e32 v237, v0
	v_sub_f32_e32 v0, v82, v233
	v_exp_f32_e32 v82, v0
	v_sub_f32_e32 v0, v83, v233
	v_exp_f32_e32 v0, v0
	v_add_f32_e32 v83, v236, v237
	v_pk_add_f32 v[80:81], v[82:83], v[0:1]
	s_nop 0
	v_pk_add_f32 v[234:235], v[80:81], v[80:81] op_sel_hi:[0,1]
	v_sub_f32_e32 v80, v84, v233
	v_exp_f32_e32 v238, v80
	v_sub_f32_e32 v80, v85, v233
	v_exp_f32_e32 v239, v80
	v_sub_f32_e32 v80, v86, v233
	v_exp_f32_e32 v84, v80
	v_sub_f32_e32 v80, v87, v233
	v_exp_f32_e32 v234, v80
	v_add_f32_e32 v85, v238, v239
	v_cvt_pk_bf16_f32 v80, v236, v237
	v_cvt_pk_bf16_f32 v81, v82, v0
	v_pk_add_f32 v[82:83], v[84:85], v[234:235]
	v_sub_f32_e32 v0, v88, v233
	v_pk_add_f32 v[86:87], v[82:83], v[82:83] op_sel_hi:[0,1]
	v_sub_f32_e32 v82, v89, v233
	v_exp_f32_e32 v235, v82
	v_sub_f32_e32 v82, v90, v233
	v_exp_f32_e32 v0, v0
	v_exp_f32_e32 v88, v82
	v_sub_f32_e32 v82, v91, v233
	v_exp_f32_e32 v86, v82
	v_add_f32_e32 v89, v0, v235
	v_cvt_pk_bf16_f32 v82, v238, v239
	v_cvt_pk_bf16_f32 v83, v84, v234
	v_pk_add_f32 v[84:85], v[88:89], v[86:87]
	s_nop 0
	v_pk_add_f32 v[238:239], v[84:85], v[84:85] op_sel_hi:[0,1]
	v_sub_f32_e32 v84, v92, v233
	v_exp_f32_e32 v241, v84
	v_sub_f32_e32 v84, v93, v233
	v_exp_f32_e32 v242, v84
	v_sub_f32_e32 v84, v94, v233
	v_exp_f32_e32 v240, v84
	v_sub_f32_e32 v84, v95, v233
	v_exp_f32_e32 v238, v84
	v_cvt_pk_bf16_f32 v84, v0, v235
	v_cvt_pk_bf16_f32 v85, v88, v86
	v_cvt_pk_bf16_f32 v86, v241, v242
	v_cvt_pk_bf16_f32 v87, v240, v238
	s_waitcnt vmcnt(0)
	ds_read_b64_tr_b16 v[88:89], v179 offset:49152
	ds_read_b64_tr_b16 v[90:91], v180 offset:49152
	ds_read_b64_tr_b16 v[92:93], v181 offset:49152
	ds_read_b64_tr_b16 v[94:95], v182 offset:49152
	ds_read_b64_tr_b16 v[234:235], v183 offset:49152
	ds_read_b64_tr_b16 v[236:237], v184 offset:49152
	v_add_f32_e32 v241, v241, v242
	v_pk_add_f32 v[238:239], v[240:241], v[238:239]
	s_nop 0
	v_add_f32_e32 v0, v238, v239
	v_add_f32_e32 v178, v178, v0
	s_waitcnt lgkmcnt(4)
	v_mfma_f32_32x32x16_bf16 v[64:79], v[88:91], v[80:83], v[64:79]
	ds_read_b64_tr_b16 v[238:239], v223 offset:49152
	ds_read_b64_tr_b16 v[240:241], v185 offset:49152
	s_waitcnt lgkmcnt(4)
	v_mfma_f32_32x32x16_bf16 v[48:63], v[92:95], v[80:83], v[48:63]
	ds_read_b64_tr_b16 v[88:89], v186 offset:49152
	ds_read_b64_tr_b16 v[90:91], v224 offset:55296
	s_waitcnt lgkmcnt(4)
	v_mfma_f32_32x32x16_bf16 v[32:47], v[234:237], v[80:83], v[32:47]
	ds_read_b64_tr_b16 v[92:93], v187 offset:49152
	ds_read_b64_tr_b16 v[94:95], v225 offset:55296
	s_waitcnt lgkmcnt(4)
	v_mfma_f32_32x32x16_bf16 v[16:31], v[238:241], v[80:83], v[16:31]
	ds_read_b64_tr_b16 v[234:235], v188 offset:49152
	ds_read_b64_tr_b16 v[236:237], v226 offset:55296
	s_waitcnt lgkmcnt(4)
	v_mfma_f32_32x32x16_bf16 v[64:79], v[88:91], v[84:87], v[64:79]
	ds_read_b64_tr_b16 v[80:81], v189 offset:49152
	ds_read_b64_tr_b16 v[82:83], v227 offset:55296
	s_waitcnt lgkmcnt(4)
	v_mfma_f32_32x32x16_bf16 v[48:63], v[92:95], v[84:87], v[48:63]
	s_waitcnt lgkmcnt(2)
	v_mfma_f32_32x32x16_bf16 v[32:47], v[234:237], v[84:87], v[32:47]
	s_waitcnt lgkmcnt(0)
	v_mfma_f32_32x32x16_bf16 v[16:31], v[80:83], v[84:87], v[16:31]
	s_sub_i32 s4, s67, 64
	s_cmp_gt_i32 s4, s88
	s_cbranch_scc1 .LBB0_3789
	v_add_u32_e32 v0, v169, v157
	v_add_u32_e32 v84, v169, v158
	ds_read_b128 v[80:83], v0
	ds_read_b128 v[234:237], v84
	v_add_u32_e32 v0, v169, v159
	v_add_u32_e32 v84, v169, v160
	ds_read_b128 v[238:241], v0
	ds_read_b128 v[242:245], v84
	s_add_i32 s4, s89, s67
	s_waitcnt lgkmcnt(3)
	v_mfma_f32_32x32x16_bf16 v[80:95], v[80:83], v[140:143], 0
	v_add_u32_e32 v0, v169, v161
	ds_read_b128 v[246:249], v0
	s_waitcnt lgkmcnt(3)
	v_mfma_f32_32x32x16_bf16 v[80:95], v[234:237], v[136:139], v[80:95]
	v_add_u32_e32 v0, v169, v162
	ds_read_b128 v[250:253], v0
	s_waitcnt lgkmcnt(3)
	v_mfma_f32_32x32x16_bf16 v[80:95], v[238:241], v[132:135], v[80:95]
	v_add_u32_e32 v0, v169, v163
	ds_read_b128 v[234:237], v0
	s_waitcnt lgkmcnt(3)
	v_mfma_f32_32x32x16_bf16 v[80:95], v[242:245], v[128:131], v[80:95]
	v_add_u32_e32 v0, v169, v164
	ds_read_b128 v[238:241], v0
	s_waitcnt lgkmcnt(3)
	v_mfma_f32_32x32x16_bf16 v[80:95], v[246:249], v[124:127], v[80:95]
	v_add_u32_e32 v0, v169, v165
	ds_read_b128 v[242:245], v0
	s_waitcnt lgkmcnt(3)
	v_mfma_f32_32x32x16_bf16 v[80:95], v[250:253], v[120:123], v[80:95]
	v_add_u32_e32 v0, v169, v166
	ds_read_b128 v[246:249], v0
	s_waitcnt lgkmcnt(3)
	v_mfma_f32_32x32x16_bf16 v[80:95], v[234:237], v[116:119], v[80:95]
	v_add_u32_e32 v0, v169, v167
	ds_read_b128 v[250:253], v0
	s_waitcnt lgkmcnt(3)
	v_mfma_f32_32x32x16_bf16 v[80:95], v[238:241], v[112:115], v[80:95]
	v_add_u32_e32 v0, v169, v168
	ds_read_b128 v[234:237], v0
	s_waitcnt lgkmcnt(3)
	v_mfma_f32_32x32x16_bf16 v[80:95], v[242:245], v[108:111], v[80:95]
	s_waitcnt lgkmcnt(2)
	v_mfma_f32_32x32x16_bf16 v[80:95], v[246:249], v[104:107], v[80:95]
	s_waitcnt lgkmcnt(1)
	v_mfma_f32_32x32x16_bf16 v[80:95], v[250:253], v[100:103], v[80:95]
	s_waitcnt lgkmcnt(0)
	v_mfma_f32_32x32x16_bf16 v[80:95], v[234:237], v[96:99], v[80:95]
	s_cmpk_lg_i32 s4, 0x60
	s_cbranch_scc1 .LBB0_3786
	s_nop 8
	v_cndmask_b32_e64 v0, v80, v150, s[8:9]
	v_cndmask_b32_e64 v81, v150, v81, s[10:11]
	v_cndmask_b32_e64 v80, v0, v80, s[10:11]
	v_cndmask_b32_e64 v82, v82, v150, s[12:13]
	v_cndmask_b32_e64 v83, v83, v150, s[14:15]
	v_cndmask_b32_e64 v84, v84, v150, s[16:17]
	v_cndmask_b32_e64 v85, v85, v150, s[18:19]
	v_cndmask_b32_e64 v86, v86, v150, s[20:21]
	v_cndmask_b32_e64 v87, v87, v150, s[22:23]
	v_cndmask_b32_e64 v88, v88, v150, s[24:25]
	v_cndmask_b32_e64 v89, v89, v150, s[26:27]
	v_cndmask_b32_e64 v90, v90, v150, s[28:29]
	v_cndmask_b32_e64 v91, v91, v150, s[30:31]
	v_cndmask_b32_e64 v92, v92, v150, s[34:35]
	v_cndmask_b32_e64 v93, v93, v150, s[36:37]
	v_cndmask_b32_e64 v94, v94, v150, s[38:39]
	v_cndmask_b32_e64 v95, v95, v150, s[40:41]

.LBB0_3788:
	v_sub_f32_e32 v0, v80, v233
	v_exp_f32_e32 v236, v0
	v_sub_f32_e32 v0, v81, v233
	v_exp_f32_e32 v237, v0
	v_sub_f32_e32 v0, v82, v233
	v_exp_f32_e32 v82, v0
	v_sub_f32_e32 v0, v83, v233
	v_exp_f32_e32 v0, v0
	v_add_f32_e32 v83, v236, v237
	v_pk_add_f32 v[80:81], v[82:83], v[0:1]
	s_nop 0
	v_pk_add_f32 v[234:235], v[80:81], v[80:81] op_sel_hi:[0,1]
	v_sub_f32_e32 v80, v84, v233
	v_exp_f32_e32 v238, v80
	v_sub_f32_e32 v80, v85, v233
	v_exp_f32_e32 v239, v80
	v_sub_f32_e32 v80, v86, v233
	v_exp_f32_e32 v84, v80
	v_sub_f32_e32 v80, v87, v233
	v_exp_f32_e32 v234, v80
	v_add_f32_e32 v85, v238, v239
	v_cvt_pk_bf16_f32 v80, v236, v237
	v_cvt_pk_bf16_f32 v81, v82, v0
	v_pk_add_f32 v[82:83], v[84:85], v[234:235]
	v_sub_f32_e32 v0, v88, v233
	v_pk_add_f32 v[86:87], v[82:83], v[82:83] op_sel_hi:[0,1]
	v_sub_f32_e32 v82, v89, v233
	v_exp_f32_e32 v235, v82
	v_sub_f32_e32 v82, v90, v233
	v_exp_f32_e32 v0, v0
	v_exp_f32_e32 v88, v82
	v_sub_f32_e32 v82, v91, v233
	v_exp_f32_e32 v86, v82
	v_add_f32_e32 v89, v0, v235
	v_cvt_pk_bf16_f32 v82, v238, v239
	v_cvt_pk_bf16_f32 v83, v84, v234
	v_pk_add_f32 v[84:85], v[88:89], v[86:87]
	s_nop 0
	v_pk_add_f32 v[238:239], v[84:85], v[84:85] op_sel_hi:[0,1]
	v_sub_f32_e32 v84, v92, v233
	v_exp_f32_e32 v241, v84
	v_sub_f32_e32 v84, v93, v233
	v_exp_f32_e32 v242, v84
	v_sub_f32_e32 v84, v94, v233
	v_exp_f32_e32 v240, v84
	v_sub_f32_e32 v84, v95, v233
	v_exp_f32_e32 v238, v84
	v_cvt_pk_bf16_f32 v84, v0, v235
	v_cvt_pk_bf16_f32 v85, v88, v86
	v_cvt_pk_bf16_f32 v86, v241, v242
	v_cvt_pk_bf16_f32 v87, v240, v238
	ds_read_b64_tr_b16 v[88:89], v190 offset:49152
	ds_read_b64_tr_b16 v[90:91], v191 offset:49152
	ds_read_b64_tr_b16 v[92:93], v192 offset:49152
	ds_read_b64_tr_b16 v[94:95], v193 offset:49152
	ds_read_b64_tr_b16 v[234:235], v194 offset:49152
	ds_read_b64_tr_b16 v[236:237], v195 offset:49152
	v_add_f32_e32 v241, v241, v242
	v_pk_add_f32 v[238:239], v[240:241], v[238:239]
	s_nop 0
	v_add_f32_e32 v0, v238, v239
	v_add_f32_e32 v178, v178, v0
	s_waitcnt lgkmcnt(4)
	v_mfma_f32_32x32x16_bf16 v[64:79], v[88:91], v[80:83], v[64:79]
	ds_read_b64_tr_b16 v[238:239], v223 offset:57344
	ds_read_b64_tr_b16 v[240:241], v196 offset:59392
	s_waitcnt lgkmcnt(4)
	v_mfma_f32_32x32x16_bf16 v[48:63], v[92:95], v[80:83], v[48:63]
	ds_read_b64_tr_b16 v[88:89], v197 offset:61440
	ds_read_b64_tr_b16 v[90:91], v224 offset:63488
	s_waitcnt lgkmcnt(4)
	v_mfma_f32_32x32x16_bf16 v[32:47], v[234:237], v[80:83], v[32:47]
	ds_read_b64_tr_b16 v[92:93], v198 offset:61440
	ds_read_b64_tr_b16 v[94:95], v225 offset:63488
	s_waitcnt lgkmcnt(4)
	v_mfma_f32_32x32x16_bf16 v[16:31], v[238:241], v[80:83], v[16:31]
	ds_read_b64_tr_b16 v[234:235], v199 offset:61440
	ds_read_b64_tr_b16 v[236:237], v226 offset:63488
	s_waitcnt lgkmcnt(4)
	v_mfma_f32_32x32x16_bf16 v[64:79], v[88:91], v[84:87], v[64:79]
	ds_read_b64_tr_b16 v[80:81], v200 offset:61440
	ds_read_b64_tr_b16 v[82:83], v227 offset:63488
	s_waitcnt lgkmcnt(4)
	v_mfma_f32_32x32x16_bf16 v[48:63], v[92:95], v[84:87], v[48:63]
	s_waitcnt lgkmcnt(2)
	v_mfma_f32_32x32x16_bf16 v[32:47], v[234:237], v[84:87], v[32:47]
	s_waitcnt lgkmcnt(0)
	v_mfma_f32_32x32x16_bf16 v[16:31], v[80:83], v[84:87], v[16:31]

.LBB0_3791:
	s_sub_i32 vcc_lo, s67, 32
	s_cmp_gt_i32 vcc_lo, s88
	s_cbranch_scc1 .LBB0_3775
	ds_read_b128 v[80:83], v12 offset:24576
	ds_read_b128 v[234:237], v13 offset:24576
	ds_read_b128 v[238:241], v14 offset:24576
	ds_read_b128 v[12:15], v15 offset:24576
	s_add_i32 vcc_lo, s66, s67
	s_waitcnt lgkmcnt(0)
	v_mfma_f32_32x32x16_bf16 v[80:95], v[80:83], v[140:143], 0
	ds_read_b128 v[242:245], v11 offset:24576
	v_mfma_f32_32x32x16_bf16 v[80:95], v[234:237], v[136:139], v[80:95]
	ds_read_b128 v[246:249], v10 offset:24576
	v_mfma_f32_32x32x16_bf16 v[80:95], v[238:241], v[132:135], v[80:95]
	ds_read_b128 v[234:237], v9 offset:24576
	v_mfma_f32_32x32x16_bf16 v[80:95], v[12:15], v[128:131], v[80:95]
	ds_read_b128 v[8:11], v8 offset:24576
	s_waitcnt lgkmcnt(0)
	v_mfma_f32_32x32x16_bf16 v[80:95], v[242:245], v[124:127], v[80:95]
	ds_read_b128 v[12:15], v7 offset:24576
	v_mfma_f32_32x32x16_bf16 v[80:95], v[246:249], v[120:123], v[80:95]
	ds_read_b128 v[238:241], v6 offset:24576
	v_mfma_f32_32x32x16_bf16 v[80:95], v[234:237], v[116:119], v[80:95]
	ds_read_b128 v[4:7], v5 offset:24576
	v_mfma_f32_32x32x16_bf16 v[80:95], v[8:11], v[112:115], v[80:95]
	ds_read_b128 v[234:237], v2 offset:24576
	s_waitcnt lgkmcnt(0)
	v_mfma_f32_32x32x16_bf16 v[80:95], v[12:15], v[108:111], v[80:95]
	v_mfma_f32_32x32x16_bf16 v[80:95], v[238:241], v[104:107], v[80:95]
	v_mfma_f32_32x32x16_bf16 v[80:95], v[4:7], v[100:103], v[80:95]
	v_mfma_f32_32x32x16_bf16 v[80:95], v[234:237], v[96:99], v[80:95]
	s_cmpk_lg_i32 vcc_lo, 0x60
	s_cbranch_scc1 .LBB0_3794
	s_nop 8
	v_cndmask_b32_e64 v0, v80, v150, s[8:9]
	v_cndmask_b32_e64 v81, v150, v81, s[10:11]
	v_cndmask_b32_e64 v80, v0, v80, s[10:11]
	v_cndmask_b32_e64 v82, v82, v150, s[12:13]
	v_cndmask_b32_e64 v83, v83, v150, s[14:15]
	v_cndmask_b32_e64 v84, v84, v150, s[16:17]
	v_cndmask_b32_e64 v85, v85, v150, s[18:19]
	v_cndmask_b32_e64 v86, v86, v150, s[20:21]
	v_cndmask_b32_e64 v87, v87, v150, s[22:23]
	v_cndmask_b32_e64 v88, v88, v150, s[24:25]
	v_cndmask_b32_e64 v89, v89, v150, s[26:27]
	v_cndmask_b32_e64 v90, v90, v150, s[28:29]
	v_cndmask_b32_e64 v91, v91, v150, s[30:31]
	v_cndmask_b32_e64 v92, v92, v150, s[34:35]
	v_cndmask_b32_e64 v93, v93, v150, s[36:37]
	v_cndmask_b32_e64 v94, v94, v150, s[38:39]
	v_cndmask_b32_e64 v95, v95, v150, s[40:41]

.LBB0_3796:
	v_sub_f32_e32 v0, v80, v233
	v_exp_f32_e32 v9, v0
	v_sub_f32_e32 v0, v81, v233
	v_exp_f32_e32 v10, v0
	v_sub_f32_e32 v0, v82, v233
	v_exp_f32_e32 v4, v0
	v_sub_f32_e32 v0, v83, v233
	v_exp_f32_e32 v0, v0
	v_add_f32_e32 v5, v9, v10
	v_pk_add_f32 v[2:3], v[4:5], v[0:1]
	s_nop 0
	v_pk_add_f32 v[6:7], v[2:3], v[2:3] op_sel_hi:[0,1]
	v_sub_f32_e32 v2, v84, v233
	v_exp_f32_e32 v13, v2
	v_sub_f32_e32 v2, v85, v233
	v_exp_f32_e32 v14, v2
	v_sub_f32_e32 v2, v86, v233
	v_exp_f32_e32 v8, v2
	v_sub_f32_e32 v2, v87, v233
	v_exp_f32_e32 v6, v2
	v_cvt_pk_bf16_f32 v2, v9, v10
	v_add_f32_e32 v9, v13, v14
	v_cvt_pk_bf16_f32 v3, v4, v0
	v_pk_add_f32 v[4:5], v[8:9], v[6:7]
	v_sub_f32_e32 v0, v88, v233
	v_pk_add_f32 v[10:11], v[4:5], v[4:5] op_sel_hi:[0,1]
	v_sub_f32_e32 v4, v89, v233
	v_exp_f32_e32 v9, v4
	v_sub_f32_e32 v4, v90, v233
	v_exp_f32_e32 v0, v0
	v_exp_f32_e32 v12, v4
	v_sub_f32_e32 v4, v91, v233
	v_exp_f32_e32 v10, v4
	v_cvt_pk_bf16_f32 v4, v13, v14
	v_add_f32_e32 v13, v0, v9
	v_cvt_pk_bf16_f32 v5, v8, v6
	v_pk_add_f32 v[6:7], v[12:13], v[10:11]
	s_nop 0
	v_pk_add_f32 v[14:15], v[6:7], v[6:7] op_sel_hi:[0,1]
	v_sub_f32_e32 v6, v92, v233
	v_exp_f32_e32 v89, v6
	v_sub_f32_e32 v6, v93, v233
	v_exp_f32_e32 v90, v6
	v_sub_f32_e32 v6, v94, v233
	v_exp_f32_e32 v88, v6
	v_sub_f32_e32 v6, v95, v233
	v_exp_f32_e32 v14, v6
	v_cvt_pk_bf16_f32 v6, v0, v9
	v_cvt_pk_bf16_f32 v7, v12, v10
	v_cvt_pk_bf16_f32 v8, v89, v90
	v_cvt_pk_bf16_f32 v9, v88, v14
	s_waitcnt vmcnt(0)
	ds_read_b64_tr_b16 v[10:11], v201
	ds_read_b64_tr_b16 v[12:13], v202
	ds_read_b64_tr_b16 v[80:81], v203
	ds_read_b64_tr_b16 v[82:83], v204
	ds_read_b64_tr_b16 v[84:85], v205
	ds_read_b64_tr_b16 v[86:87], v206
	v_add_f32_e32 v89, v89, v90
	v_pk_add_f32 v[14:15], v[88:89], v[14:15]
	s_nop 0
	v_add_f32_e32 v0, v14, v15
	v_add_f32_e32 v178, v178, v0
	s_waitcnt lgkmcnt(4)
	v_mfma_f32_32x32x16_bf16 v[64:79], v[10:13], v[2:5], v[64:79]
	ds_read_b64_tr_b16 v[88:89], v228
	ds_read_b64_tr_b16 v[90:91], v207
	s_waitcnt lgkmcnt(4)
	v_mfma_f32_32x32x16_bf16 v[48:63], v[80:83], v[2:5], v[48:63]
	ds_read_b64_tr_b16 v[10:11], v208
	ds_read_b64_tr_b16 v[12:13], v229 offset:6144
	s_waitcnt lgkmcnt(4)
	v_mfma_f32_32x32x16_bf16 v[32:47], v[84:87], v[2:5], v[32:47]
	ds_read_b64_tr_b16 v[80:81], v209
	ds_read_b64_tr_b16 v[82:83], v230 offset:6144
	s_waitcnt lgkmcnt(4)
	v_mfma_f32_32x32x16_bf16 v[16:31], v[88:91], v[2:5], v[16:31]
	ds_read_b64_tr_b16 v[84:85], v210
	ds_read_b64_tr_b16 v[86:87], v231 offset:6144
	s_waitcnt lgkmcnt(4)
	v_mfma_f32_32x32x16_bf16 v[64:79], v[10:13], v[6:9], v[64:79]
	ds_read_b64_tr_b16 v[2:3], v211
	ds_read_b64_tr_b16 v[4:5], v232 offset:6144
	s_waitcnt lgkmcnt(4)
	v_mfma_f32_32x32x16_bf16 v[48:63], v[80:83], v[6:9], v[48:63]
	s_waitcnt lgkmcnt(2)
	v_mfma_f32_32x32x16_bf16 v[32:47], v[84:87], v[6:9], v[32:47]
	s_waitcnt lgkmcnt(0)
	v_mfma_f32_32x32x16_bf16 v[16:31], v[2:5], v[6:9], v[16:31]
	s_cmp_gt_i32 s67, s88
	s_cbranch_scc1 .LBB0_3775
	v_add_u32_e32 v0, v169, v157
	v_add_u32_e32 v6, v169, v158
	ds_read_b128 v[2:5], v0 offset:24576
	ds_read_b128 v[6:9], v6 offset:24576
	v_add_u32_e32 v0, v169, v159
	v_add_u32_e32 v14, v169, v160
	ds_read_b128 v[10:13], v0 offset:24576
	ds_read_b128 v[234:237], v14 offset:24576
	s_waitcnt lgkmcnt(3)
	v_mfma_f32_32x32x16_bf16 v[80:95], v[2:5], v[140:143], 0
	v_add_u32_e32 v0, v169, v161
	ds_read_b128 v[238:241], v0 offset:24576
	s_waitcnt lgkmcnt(3)
	v_mfma_f32_32x32x16_bf16 v[80:95], v[6:9], v[136:139], v[80:95]
	v_add_u32_e32 v0, v169, v162
	ds_read_b128 v[2:5], v0 offset:24576
	s_waitcnt lgkmcnt(3)
	v_mfma_f32_32x32x16_bf16 v[80:95], v[10:13], v[132:135], v[80:95]
	v_add_u32_e32 v0, v169, v163
	ds_read_b128 v[6:9], v0 offset:24576
	s_waitcnt lgkmcnt(3)
	v_mfma_f32_32x32x16_bf16 v[80:95], v[234:237], v[128:131], v[80:95]
	v_add_u32_e32 v0, v169, v164
	ds_read_b128 v[10:13], v0 offset:24576
	s_waitcnt lgkmcnt(3)
	v_mfma_f32_32x32x16_bf16 v[80:95], v[238:241], v[124:127], v[80:95]
	v_add_u32_e32 v0, v169, v165
	ds_read_b128 v[234:237], v0 offset:24576
	s_waitcnt lgkmcnt(3)
	v_mfma_f32_32x32x16_bf16 v[80:95], v[2:5], v[120:123], v[80:95]
	v_add_u32_e32 v0, v169, v166
	ds_read_b128 v[238:241], v0 offset:24576
	s_waitcnt lgkmcnt(3)
	v_mfma_f32_32x32x16_bf16 v[80:95], v[6:9], v[116:119], v[80:95]
	v_add_u32_e32 v0, v169, v167
	ds_read_b128 v[2:5], v0 offset:24576
	s_waitcnt lgkmcnt(3)
	v_mfma_f32_32x32x16_bf16 v[80:95], v[10:13], v[112:115], v[80:95]
	v_add_u32_e32 v0, v169, v168
	ds_read_b128 v[6:9], v0 offset:24576
	s_waitcnt lgkmcnt(3)
	v_mfma_f32_32x32x16_bf16 v[80:95], v[234:237], v[108:111], v[80:95]
	s_waitcnt lgkmcnt(2)
	v_mfma_f32_32x32x16_bf16 v[80:95], v[238:241], v[104:107], v[80:95]
	s_waitcnt lgkmcnt(1)
	v_mfma_f32_32x32x16_bf16 v[80:95], v[2:5], v[100:103], v[80:95]
	s_waitcnt lgkmcnt(0)
	v_mfma_f32_32x32x16_bf16 v[80:95], v[6:9], v[96:99], v[80:95]
	s_cmp_lg_u32 s84, 0
	s_cbranch_scc1 .LBB0_3799
	s_nop 8
	v_cndmask_b32_e64 v0, v80, v150, s[8:9]
	v_cndmask_b32_e64 v81, v150, v81, s[10:11]
	v_cndmask_b32_e64 v80, v0, v80, s[10:11]
	v_cndmask_b32_e64 v82, v82, v150, s[12:13]
	v_cndmask_b32_e64 v83, v83, v150, s[14:15]
	v_cndmask_b32_e64 v84, v84, v150, s[16:17]
	v_cndmask_b32_e64 v85, v85, v150, s[18:19]
	v_cndmask_b32_e64 v86, v86, v150, s[20:21]
	v_cndmask_b32_e64 v87, v87, v150, s[22:23]
	v_cndmask_b32_e64 v88, v88, v150, s[24:25]
	v_cndmask_b32_e64 v89, v89, v150, s[26:27]
	v_cndmask_b32_e64 v90, v90, v150, s[28:29]
	v_cndmask_b32_e64 v91, v91, v150, s[30:31]
	v_cndmask_b32_e64 v92, v92, v150, s[34:35]
	v_cndmask_b32_e64 v93, v93, v150, s[36:37]
	v_cndmask_b32_e64 v94, v94, v150, s[38:39]
	v_cndmask_b32_e64 v95, v95, v150, s[40:41]
